# residual epilogues: base-load wait moved into the load block so K-slice units stream their stores
# baseline (speedup 1.0000x reference)
.LBB0_323:
	s_lshl_b32 s34, s68, 8
	s_add_i32 s27, s34, 0xffffc000
	s_and_b64 s[6:7], s[42:43], exec
	s_cselect_b32 s6, s27, s34
	v_add_u32_e32 v184, s6, v1
	v_ashrrev_i32_e32 v185, 31, v184
	v_lshlrev_b64 v[132:133], 10, v[184:185]
	v_lshl_add_u64 v[158:159], v[132:133], 0, v[154:155]
	v_cndmask_b32_e64 v131, 0, 1, s[36:37]
	v_cmp_ne_u32_e64 s[6:7], 1, v131
	s_andn2_b64 vcc, exec, s[36:37]
	v_lshl_add_u64 v[170:171], v[158:159], 2, s[14:15]
	v_mov_b32_e32 v131, 0
	v_mov_b32_e32 v132, 0
	v_mov_b32_e32 v133, 0
	v_mov_b32_e32 v134, 0
	v_mov_b32_e32 v135, 0
	v_mov_b32_e32 v136, 0
	v_mov_b32_e32 v137, 0
	s_cbranch_vccnz .LBB0_325
	global_load_dwordx4 v[130:133], v[170:171], off
	global_load_dwordx4 v[134:137], v[170:171], off offset:16
	s_waitcnt vmcnt(0)
.LBB0_325:
	v_add_u32_e32 v156, s34, v1
	v_pk_fma_f32 v[76:77], v[76:77], v[196:197], v[132:133]
	v_pk_fma_f32 v[74:75], v[74:75], v[192:193], v[130:131]
	v_pk_fma_f32 v[80:81], v[80:81], v[186:187], v[136:137]
	v_pk_fma_f32 v[78:79], v[78:79], v[182:183], v[134:135]
	v_lshl_add_u64 v[178:179], v[158:159], 2, s[40:41]
	s_and_b64 vcc, exec, s[4:5]
	v_ashrrev_i32_e32 v157, 31, v156
	global_store_dwordx4 v[178:179], v[74:77], off
	global_store_dwordx4 v[178:179], v[78:81], off offset:16
	s_cbranch_vccnz .LBB0_327
	v_pk_mul_f32 v[132:133], v[220:221], v[76:77]
	v_pk_mul_f32 v[130:131], v[218:219], v[74:75]
	v_pk_mul_f32 v[134:135], v[216:217], v[80:81]
	v_cvt_pk_bf16_f32 v130, v130, v131
	v_cvt_pk_bf16_f32 v131, v132, v133
	v_cvt_pk_bf16_f32 v133, v134, v135
	v_lshlrev_b64 v[134:135], 11, v[156:157]
	v_pk_mul_f32 v[136:137], v[214:215], v[78:79]
	v_lshl_add_u64 v[134:135], s[20:21], 0, v[134:135]
	v_cvt_pk_bf16_f32 v132, v136, v137
	v_lshl_add_u64 v[134:135], v[154:155], 1, v[134:135]
	global_store_dwordx4 v[134:135], v[130:133], off
.LBB0_327:
	s_nop 1
	v_or_b32_e32 v130, 16, v184
	v_ashrrev_i32_e32 v131, 31, v130
	v_lshlrev_b64 v[130:131], 10, v[130:131]
	v_lshl_add_u64 v[160:161], v[130:131], 0, v[154:155]
	v_mov_b32_e32 v134, 0
	s_and_b64 vcc, exec, s[6:7]
	v_lshl_add_u64 v[174:175], v[160:161], 2, s[14:15]
	v_mov_b32_e32 v135, 0
	v_mov_b32_e32 v136, 0
	v_mov_b32_e32 v137, 0
	v_mov_b32_e32 v130, 0
	v_mov_b32_e32 v131, 0
	v_mov_b32_e32 v132, 0
	v_mov_b32_e32 v133, 0
	s_cbranch_vccnz .LBB0_329
	global_load_dwordx4 v[134:137], v[174:175], off
	global_load_dwordx4 v[130:133], v[174:175], off offset:16
	s_waitcnt vmcnt(0)
.LBB0_329:
	v_add_u32_e32 v158, s34, v237
	v_pk_fma_f32 v[92:93], v[92:93], v[196:197], v[136:137]
	v_pk_fma_f32 v[90:91], v[90:91], v[192:193], v[134:135]
	v_pk_fma_f32 v[96:97], v[96:97], v[186:187], v[132:133]
	v_pk_fma_f32 v[94:95], v[94:95], v[182:183], v[130:131]
	v_lshl_add_u64 v[188:189], v[160:161], 2, s[40:41]
	s_and_b64 vcc, exec, s[4:5]
	v_ashrrev_i32_e32 v159, 31, v158
	global_store_dwordx4 v[188:189], v[90:93], off
	global_store_dwordx4 v[188:189], v[94:97], off offset:16
	s_cbranch_vccnz .LBB0_331
	v_pk_mul_f32 v[132:133], v[220:221], v[92:93]
	v_pk_mul_f32 v[130:131], v[218:219], v[90:91]
	v_pk_mul_f32 v[134:135], v[216:217], v[96:97]
	v_cvt_pk_bf16_f32 v130, v130, v131
	v_cvt_pk_bf16_f32 v131, v132, v133
	v_cvt_pk_bf16_f32 v133, v134, v135
	v_lshlrev_b64 v[134:135], 11, v[158:159]
	v_pk_mul_f32 v[136:137], v[214:215], v[94:95]
	v_lshl_add_u64 v[134:135], s[20:21], 0, v[134:135]
	v_cvt_pk_bf16_f32 v132, v136, v137
	v_lshl_add_u64 v[134:135], v[154:155], 1, v[134:135]
	global_store_dwordx4 v[134:135], v[130:133], off
.LBB0_331:
	s_nop 1
	v_or_b32_e32 v130, 32, v184
	v_ashrrev_i32_e32 v131, 31, v130
	v_lshlrev_b64 v[130:131], 10, v[130:131]
	v_lshl_add_u64 v[166:167], v[130:131], 0, v[154:155]
	v_mov_b32_e32 v134, 0
	s_and_b64 vcc, exec, s[6:7]
	v_lshl_add_u64 v[180:181], v[166:167], 2, s[14:15]
	v_mov_b32_e32 v135, 0
	v_mov_b32_e32 v136, 0
	v_mov_b32_e32 v137, 0
	v_mov_b32_e32 v130, 0
	v_mov_b32_e32 v131, 0
	v_mov_b32_e32 v132, 0
	v_mov_b32_e32 v133, 0
	s_cbranch_vccnz .LBB0_333
	global_load_dwordx4 v[134:137], v[180:181], off
	global_load_dwordx4 v[130:133], v[180:181], off offset:16
	s_waitcnt vmcnt(0)
.LBB0_333:
	v_add_u32_e32 v160, s34, v238
	v_pk_fma_f32 v[100:101], v[100:101], v[196:197], v[136:137]
	v_pk_fma_f32 v[98:99], v[98:99], v[192:193], v[134:135]
	v_pk_fma_f32 v[104:105], v[104:105], v[186:187], v[132:133]
	v_pk_fma_f32 v[102:103], v[102:103], v[182:183], v[130:131]
	v_lshl_add_u64 v[194:195], v[166:167], 2, s[40:41]
	s_and_b64 vcc, exec, s[4:5]
	v_ashrrev_i32_e32 v161, 31, v160
	global_store_dwordx4 v[194:195], v[98:101], off
	global_store_dwordx4 v[194:195], v[102:105], off offset:16
	s_cbranch_vccnz .LBB0_335
	v_pk_mul_f32 v[132:133], v[220:221], v[100:101]
	v_pk_mul_f32 v[130:131], v[218:219], v[98:99]
	v_pk_mul_f32 v[134:135], v[216:217], v[104:105]
	v_cvt_pk_bf16_f32 v130, v130, v131
	v_cvt_pk_bf16_f32 v131, v132, v133
	v_cvt_pk_bf16_f32 v133, v134, v135
	v_lshlrev_b64 v[134:135], 11, v[160:161]
	v_pk_mul_f32 v[136:137], v[214:215], v[102:103]
	v_lshl_add_u64 v[134:135], s[20:21], 0, v[134:135]
	v_cvt_pk_bf16_f32 v132, v136, v137
	v_lshl_add_u64 v[134:135], v[154:155], 1, v[134:135]
	global_store_dwordx4 v[134:135], v[130:133], off
.LBB0_335:
	s_nop 1
	v_or_b32_e32 v130, 48, v184
	v_ashrrev_i32_e32 v131, 31, v130
	v_lshlrev_b64 v[130:131], 10, v[130:131]
	v_lshl_add_u64 v[168:169], v[130:131], 0, v[154:155]
	v_mov_b32_e32 v134, 0
	s_and_b64 vcc, exec, s[6:7]
	v_lshl_add_u64 v[190:191], v[168:169], 2, s[14:15]
	v_mov_b32_e32 v135, 0
	v_mov_b32_e32 v136, 0
	v_mov_b32_e32 v137, 0
	v_mov_b32_e32 v130, 0
	v_mov_b32_e32 v131, 0
	v_mov_b32_e32 v132, 0
	v_mov_b32_e32 v133, 0
	s_cbranch_vccnz .LBB0_337
	global_load_dwordx4 v[134:137], v[190:191], off
	global_load_dwordx4 v[130:133], v[190:191], off offset:16
	s_waitcnt vmcnt(0)
.LBB0_337:
	v_add_u32_e32 v166, s34, v239
	v_pk_fma_f32 v[116:117], v[116:117], v[196:197], v[136:137]
	v_pk_fma_f32 v[114:115], v[114:115], v[192:193], v[134:135]
	v_pk_fma_f32 v[120:121], v[120:121], v[186:187], v[132:133]
	v_pk_fma_f32 v[118:119], v[118:119], v[182:183], v[130:131]
	v_lshl_add_u64 v[200:201], v[168:169], 2, s[40:41]
	s_and_b64 vcc, exec, s[4:5]
	v_ashrrev_i32_e32 v167, 31, v166
	global_store_dwordx4 v[200:201], v[114:117], off
	global_store_dwordx4 v[200:201], v[118:121], off offset:16
	s_cbranch_vccnz .LBB0_339
	v_pk_mul_f32 v[132:133], v[220:221], v[116:117]
	v_pk_mul_f32 v[130:131], v[218:219], v[114:115]
	v_pk_mul_f32 v[134:135], v[216:217], v[120:121]
	v_cvt_pk_bf16_f32 v130, v130, v131
	v_cvt_pk_bf16_f32 v131, v132, v133
	v_cvt_pk_bf16_f32 v133, v134, v135
	v_lshlrev_b64 v[134:135], 11, v[166:167]
	v_pk_mul_f32 v[136:137], v[214:215], v[118:119]
	v_lshl_add_u64 v[134:135], s[20:21], 0, v[134:135]
	v_cvt_pk_bf16_f32 v132, v136, v137
	v_lshl_add_u64 v[134:135], v[154:155], 1, v[134:135]
	global_store_dwordx4 v[134:135], v[130:133], off
.LBB0_339:
	s_nop 1
	v_add_u32_e32 v130, 0x80, v184
	v_ashrrev_i32_e32 v131, 31, v130
	v_lshlrev_b64 v[130:131], 10, v[130:131]
	v_lshl_add_u64 v[172:173], v[130:131], 0, v[154:155]
	v_mov_b32_e32 v134, 0
	s_and_b64 vcc, exec, s[6:7]
	v_lshl_add_u64 v[198:199], v[172:173], 2, s[14:15]
	v_mov_b32_e32 v135, 0
	v_mov_b32_e32 v136, 0
	v_mov_b32_e32 v137, 0
	v_mov_b32_e32 v130, 0
	v_mov_b32_e32 v131, 0
	v_mov_b32_e32 v132, 0
	v_mov_b32_e32 v133, 0
	s_cbranch_vccnz .LBB0_341
	global_load_dwordx4 v[134:137], v[198:199], off
	global_load_dwordx4 v[130:133], v[198:199], off offset:16
	s_waitcnt vmcnt(0)
.LBB0_341:
	v_add_u32_e32 v168, s34, v240
	v_pk_fma_f32 v[124:125], v[124:125], v[196:197], v[136:137]
	v_pk_fma_f32 v[122:123], v[122:123], v[192:193], v[134:135]
	v_pk_fma_f32 v[128:129], v[128:129], v[186:187], v[132:133]
	v_pk_fma_f32 v[126:127], v[126:127], v[182:183], v[130:131]
	v_lshl_add_u64 v[204:205], v[172:173], 2, s[40:41]
	s_and_b64 vcc, exec, s[4:5]
	v_ashrrev_i32_e32 v169, 31, v168
	global_store_dwordx4 v[204:205], v[122:125], off
	global_store_dwordx4 v[204:205], v[126:129], off offset:16
	s_cbranch_vccnz .LBB0_343
	v_pk_mul_f32 v[132:133], v[220:221], v[124:125]
	v_pk_mul_f32 v[130:131], v[218:219], v[122:123]
	v_pk_mul_f32 v[134:135], v[216:217], v[128:129]
	v_cvt_pk_bf16_f32 v130, v130, v131
	v_cvt_pk_bf16_f32 v131, v132, v133
	v_cvt_pk_bf16_f32 v133, v134, v135
	v_lshlrev_b64 v[134:135], 11, v[168:169]
	v_pk_mul_f32 v[136:137], v[214:215], v[126:127]
	v_lshl_add_u64 v[134:135], s[20:21], 0, v[134:135]
	v_cvt_pk_bf16_f32 v132, v136, v137
	v_lshl_add_u64 v[134:135], v[154:155], 1, v[134:135]
	global_store_dwordx4 v[134:135], v[130:133], off
.LBB0_343:
	s_nop 1
	v_add_u32_e32 v130, 0x90, v184
	v_ashrrev_i32_e32 v131, 31, v130
	v_lshlrev_b64 v[130:131], 10, v[130:131]
	v_lshl_add_u64 v[176:177], v[130:131], 0, v[154:155]
	v_mov_b32_e32 v134, 0
	s_and_b64 vcc, exec, s[6:7]
	v_lshl_add_u64 v[202:203], v[176:177], 2, s[14:15]
	v_mov_b32_e32 v135, 0
	v_mov_b32_e32 v136, 0
	v_mov_b32_e32 v137, 0
	v_mov_b32_e32 v130, 0
	v_mov_b32_e32 v131, 0
	v_mov_b32_e32 v132, 0
	v_mov_b32_e32 v133, 0
	s_cbranch_vccnz .LBB0_345
	global_load_dwordx4 v[134:137], v[202:203], off
	global_load_dwordx4 v[130:133], v[202:203], off offset:16
	s_waitcnt vmcnt(0)
.LBB0_345:
	v_add_u32_e32 v172, s34, v241
	v_pk_fma_f32 v[112:113], v[112:113], v[196:197], v[136:137]
	v_pk_fma_f32 v[110:111], v[110:111], v[192:193], v[134:135]
	v_pk_fma_f32 v[108:109], v[108:109], v[186:187], v[132:133]
	v_pk_fma_f32 v[106:107], v[106:107], v[182:183], v[130:131]
	v_lshl_add_u64 v[208:209], v[176:177], 2, s[40:41]
	s_and_b64 vcc, exec, s[4:5]
	v_ashrrev_i32_e32 v173, 31, v172
	global_store_dwordx4 v[208:209], v[110:113], off
	global_store_dwordx4 v[208:209], v[106:109], off offset:16
	s_cbranch_vccnz .LBB0_347
	v_pk_mul_f32 v[132:133], v[220:221], v[112:113]
	v_pk_mul_f32 v[130:131], v[218:219], v[110:111]
	v_pk_mul_f32 v[134:135], v[216:217], v[108:109]
	v_cvt_pk_bf16_f32 v130, v130, v131
	v_cvt_pk_bf16_f32 v131, v132, v133
	v_cvt_pk_bf16_f32 v133, v134, v135
	v_lshlrev_b64 v[134:135], 11, v[172:173]
	v_pk_mul_f32 v[136:137], v[214:215], v[106:107]
	v_lshl_add_u64 v[134:135], s[20:21], 0, v[134:135]
	v_cvt_pk_bf16_f32 v132, v136, v137
	v_lshl_add_u64 v[134:135], v[154:155], 1, v[134:135]
	global_store_dwordx4 v[134:135], v[130:133], off
.LBB0_347:
	s_nop 1
	v_add_u32_e32 v130, 0xa0, v184
	v_ashrrev_i32_e32 v131, 31, v130
	v_lshlrev_b64 v[130:131], 10, v[130:131]
	v_lshl_add_u64 v[210:211], v[130:131], 0, v[154:155]
	v_mov_b32_e32 v134, 0
	s_and_b64 vcc, exec, s[6:7]
	v_lshl_add_u64 v[206:207], v[210:211], 2, s[14:15]
	v_mov_b32_e32 v135, 0
	v_mov_b32_e32 v136, 0
	v_mov_b32_e32 v137, 0
	v_mov_b32_e32 v130, 0
	v_mov_b32_e32 v131, 0
	v_mov_b32_e32 v132, 0
	v_mov_b32_e32 v133, 0
	s_cbranch_vccnz .LBB0_349
	global_load_dwordx4 v[134:137], v[206:207], off
	global_load_dwordx4 v[130:133], v[206:207], off offset:16
	s_waitcnt vmcnt(0)
.LBB0_349:
	v_add_u32_e32 v176, s34, v242
	v_pk_fma_f32 v[88:89], v[88:89], v[196:197], v[136:137]
	v_pk_fma_f32 v[86:87], v[86:87], v[192:193], v[134:135]
	v_pk_fma_f32 v[84:85], v[84:85], v[186:187], v[132:133]
	v_pk_fma_f32 v[82:83], v[82:83], v[182:183], v[130:131]
	v_lshl_add_u64 v[212:213], v[210:211], 2, s[40:41]
	s_and_b64 vcc, exec, s[4:5]
	v_ashrrev_i32_e32 v177, 31, v176
	global_store_dwordx4 v[212:213], v[86:89], off
	global_store_dwordx4 v[212:213], v[82:85], off offset:16
	s_cbranch_vccnz .LBB0_351
	v_pk_mul_f32 v[132:133], v[220:221], v[88:89]
	v_pk_mul_f32 v[130:131], v[218:219], v[86:87]
	v_pk_mul_f32 v[134:135], v[216:217], v[84:85]
	v_cvt_pk_bf16_f32 v130, v130, v131
	v_cvt_pk_bf16_f32 v131, v132, v133
	v_cvt_pk_bf16_f32 v133, v134, v135
	v_lshlrev_b64 v[134:135], 11, v[176:177]
	v_pk_mul_f32 v[136:137], v[214:215], v[82:83]
	v_lshl_add_u64 v[134:135], s[20:21], 0, v[134:135]
	v_cvt_pk_bf16_f32 v132, v136, v137
	v_lshl_add_u64 v[134:135], v[154:155], 1, v[134:135]
	global_store_dwordx4 v[134:135], v[130:133], off
.LBB0_351:
	s_nop 1
	v_add_u32_e32 v130, 0xb0, v184
	v_ashrrev_i32_e32 v131, 31, v130
	v_lshlrev_b64 v[130:131], 10, v[130:131]
	v_lshl_add_u64 v[222:223], v[130:131], 0, v[154:155]
	v_mov_b32_e32 v134, 0
	s_and_b64 vcc, exec, s[6:7]
	v_lshl_add_u64 v[210:211], v[222:223], 2, s[14:15]
	v_mov_b32_e32 v135, 0
	v_mov_b32_e32 v136, 0
	v_mov_b32_e32 v137, 0
	v_mov_b32_e32 v130, 0
	v_mov_b32_e32 v131, 0
	v_mov_b32_e32 v132, 0
	v_mov_b32_e32 v133, 0
	s_cbranch_vccnz .LBB0_353
	global_load_dwordx4 v[134:137], v[210:211], off
	global_load_dwordx4 v[130:133], v[210:211], off offset:16
	s_waitcnt vmcnt(0)
.LBB0_353:
	v_add_u32_e32 v184, s34, v243
	v_pk_fma_f32 v[72:73], v[72:73], v[196:197], v[136:137]
	v_pk_fma_f32 v[70:71], v[70:71], v[192:193], v[134:135]
	v_pk_fma_f32 v[68:69], v[68:69], v[186:187], v[132:133]
	v_pk_fma_f32 v[66:67], v[66:67], v[182:183], v[130:131]
	v_lshl_add_u64 v[182:183], v[222:223], 2, s[40:41]
	s_and_b64 vcc, exec, s[4:5]
	v_ashrrev_i32_e32 v185, 31, v184
	global_store_dwordx4 v[182:183], v[70:73], off
	global_store_dwordx4 v[182:183], v[66:69], off offset:16
	s_cbranch_vccnz .LBB0_355
	v_pk_mul_f32 v[132:133], v[220:221], v[72:73]
	v_pk_mul_f32 v[130:131], v[218:219], v[70:71]
	v_pk_mul_f32 v[134:135], v[216:217], v[68:69]
	v_cvt_pk_bf16_f32 v130, v130, v131
	v_cvt_pk_bf16_f32 v131, v132, v133
	v_cvt_pk_bf16_f32 v133, v134, v135
	v_lshlrev_b64 v[134:135], 11, v[184:185]
	v_pk_mul_f32 v[136:137], v[214:215], v[66:67]
	v_lshl_add_u64 v[134:135], s[20:21], 0, v[134:135]
	v_cvt_pk_bf16_f32 v132, v136, v137
	v_lshl_add_u64 v[134:135], v[154:155], 1, v[134:135]
	global_store_dwordx4 v[134:135], v[130:133], off

.LBB0_359:
	s_and_b64 vcc, exec, s[6:7]
	v_mov_b32_e32 v131, 0
	v_mov_b32_e32 v132, 0
	v_mov_b32_e32 v133, 0
	v_mov_b32_e32 v134, 0
	v_mov_b32_e32 v135, 0
	v_mov_b32_e32 v136, 0
	v_mov_b32_e32 v137, 0
	s_cbranch_vccnz .LBB0_361
	global_load_dwordx4 v[130:133], v[170:171], off offset:512
	global_load_dwordx4 v[134:137], v[170:171], off offset:528
	s_waitcnt vmcnt(0)
.LBB0_361:
	v_pk_fma_f32 v[64:65], v[64:65], v[214:215], v[132:133]
	v_pk_fma_f32 v[62:63], v[62:63], v[196:197], v[130:131]
	v_pk_fma_f32 v[60:61], v[60:61], v[192:193], v[136:137]
	v_pk_fma_f32 v[58:59], v[58:59], v[186:187], v[134:135]
	s_and_b64 vcc, exec, s[4:5]
	global_store_dwordx4 v[178:179], v[62:65], off offset:512
	global_store_dwordx4 v[178:179], v[58:61], off offset:528
	s_cbranch_vccnz .LBB0_363
	v_pk_mul_f32 v[132:133], v[222:223], v[64:65]
	v_pk_mul_f32 v[130:131], v[220:221], v[62:63]
	v_pk_mul_f32 v[134:135], v[218:219], v[60:61]
	v_cvt_pk_bf16_f32 v130, v130, v131
	v_cvt_pk_bf16_f32 v131, v132, v133
	v_cvt_pk_bf16_f32 v133, v134, v135
	v_lshlrev_b64 v[134:135], 11, v[156:157]
	v_pk_mul_f32 v[136:137], v[216:217], v[58:59]
	v_lshl_add_u64 v[134:135], s[20:21], 0, v[134:135]
	v_cvt_pk_bf16_f32 v132, v136, v137
	v_lshl_add_u64 v[134:135], v[154:155], 1, v[134:135]
	global_store_dwordx4 v[134:135], v[130:133], off offset:256
.LBB0_363:
	v_mov_b32_e32 v134, 0
	s_and_b64 vcc, exec, s[6:7]
	v_mov_b32_e32 v135, 0
	v_mov_b32_e32 v136, 0
	v_mov_b32_e32 v137, 0
	v_mov_b32_e32 v130, 0
	v_mov_b32_e32 v131, 0
	v_mov_b32_e32 v132, 0
	v_mov_b32_e32 v133, 0
	s_cbranch_vccnz .LBB0_365
	global_load_dwordx4 v[134:137], v[174:175], off offset:512
	global_load_dwordx4 v[130:133], v[174:175], off offset:528
	s_waitcnt vmcnt(0)
.LBB0_365:
	v_pk_fma_f32 v[56:57], v[56:57], v[214:215], v[136:137]
	v_pk_fma_f32 v[54:55], v[54:55], v[196:197], v[134:135]
	v_pk_fma_f32 v[52:53], v[52:53], v[192:193], v[132:133]
	v_pk_fma_f32 v[50:51], v[50:51], v[186:187], v[130:131]
	s_and_b64 vcc, exec, s[4:5]
	global_store_dwordx4 v[188:189], v[54:57], off offset:512
	global_store_dwordx4 v[188:189], v[50:53], off offset:528
	s_cbranch_vccnz .LBB0_367
	v_pk_mul_f32 v[132:133], v[222:223], v[56:57]
	v_pk_mul_f32 v[130:131], v[220:221], v[54:55]
	v_pk_mul_f32 v[134:135], v[218:219], v[52:53]
	v_cvt_pk_bf16_f32 v130, v130, v131
	v_cvt_pk_bf16_f32 v131, v132, v133
	v_cvt_pk_bf16_f32 v133, v134, v135
	v_lshlrev_b64 v[134:135], 11, v[158:159]
	v_pk_mul_f32 v[136:137], v[216:217], v[50:51]
	v_lshl_add_u64 v[134:135], s[20:21], 0, v[134:135]
	v_cvt_pk_bf16_f32 v132, v136, v137
	v_lshl_add_u64 v[134:135], v[154:155], 1, v[134:135]
	global_store_dwordx4 v[134:135], v[130:133], off offset:256
.LBB0_367:
	v_mov_b32_e32 v134, 0
	s_and_b64 vcc, exec, s[6:7]
	v_mov_b32_e32 v135, 0
	v_mov_b32_e32 v136, 0
	v_mov_b32_e32 v137, 0
	v_mov_b32_e32 v130, 0
	v_mov_b32_e32 v131, 0
	v_mov_b32_e32 v132, 0
	v_mov_b32_e32 v133, 0
	s_cbranch_vccnz .LBB0_369
	global_load_dwordx4 v[134:137], v[180:181], off offset:512
	global_load_dwordx4 v[130:133], v[180:181], off offset:528
	s_waitcnt vmcnt(0)
.LBB0_369:
	v_pk_fma_f32 v[48:49], v[48:49], v[214:215], v[136:137]
	v_pk_fma_f32 v[46:47], v[46:47], v[196:197], v[134:135]
	v_pk_fma_f32 v[44:45], v[44:45], v[192:193], v[132:133]
	v_pk_fma_f32 v[42:43], v[42:43], v[186:187], v[130:131]
	s_and_b64 vcc, exec, s[4:5]
	global_store_dwordx4 v[194:195], v[46:49], off offset:512
	global_store_dwordx4 v[194:195], v[42:45], off offset:528
	s_cbranch_vccnz .LBB0_371
	v_pk_mul_f32 v[132:133], v[222:223], v[48:49]
	v_pk_mul_f32 v[130:131], v[220:221], v[46:47]
	v_pk_mul_f32 v[134:135], v[218:219], v[44:45]
	v_cvt_pk_bf16_f32 v130, v130, v131
	v_cvt_pk_bf16_f32 v131, v132, v133
	v_cvt_pk_bf16_f32 v133, v134, v135
	v_lshlrev_b64 v[134:135], 11, v[160:161]
	v_pk_mul_f32 v[136:137], v[216:217], v[42:43]
	v_lshl_add_u64 v[134:135], s[20:21], 0, v[134:135]
	v_cvt_pk_bf16_f32 v132, v136, v137
	v_lshl_add_u64 v[134:135], v[154:155], 1, v[134:135]
	global_store_dwordx4 v[134:135], v[130:133], off offset:256
.LBB0_371:
	v_mov_b32_e32 v134, 0
	s_and_b64 vcc, exec, s[6:7]
	v_mov_b32_e32 v135, 0
	v_mov_b32_e32 v136, 0
	v_mov_b32_e32 v137, 0
	v_mov_b32_e32 v130, 0
	v_mov_b32_e32 v131, 0
	v_mov_b32_e32 v132, 0
	v_mov_b32_e32 v133, 0
	s_cbranch_vccnz .LBB0_373
	global_load_dwordx4 v[134:137], v[190:191], off offset:512
	global_load_dwordx4 v[130:133], v[190:191], off offset:528
	s_waitcnt vmcnt(0)
.LBB0_373:
	v_pk_fma_f32 v[40:41], v[40:41], v[214:215], v[136:137]
	v_pk_fma_f32 v[38:39], v[38:39], v[196:197], v[134:135]
	v_pk_fma_f32 v[36:37], v[36:37], v[192:193], v[132:133]
	v_pk_fma_f32 v[34:35], v[34:35], v[186:187], v[130:131]
	s_and_b64 vcc, exec, s[4:5]
	global_store_dwordx4 v[200:201], v[38:41], off offset:512
	global_store_dwordx4 v[200:201], v[34:37], off offset:528
	s_cbranch_vccnz .LBB0_375
	v_pk_mul_f32 v[132:133], v[222:223], v[40:41]
	v_pk_mul_f32 v[130:131], v[220:221], v[38:39]
	v_pk_mul_f32 v[134:135], v[218:219], v[36:37]
	v_cvt_pk_bf16_f32 v130, v130, v131
	v_cvt_pk_bf16_f32 v131, v132, v133
	v_cvt_pk_bf16_f32 v133, v134, v135
	v_lshlrev_b64 v[134:135], 11, v[166:167]
	v_pk_mul_f32 v[136:137], v[216:217], v[34:35]
	v_lshl_add_u64 v[134:135], s[20:21], 0, v[134:135]
	v_cvt_pk_bf16_f32 v132, v136, v137
	v_lshl_add_u64 v[134:135], v[154:155], 1, v[134:135]
	global_store_dwordx4 v[134:135], v[130:133], off offset:256
.LBB0_375:
	v_mov_b32_e32 v134, 0
	s_and_b64 vcc, exec, s[6:7]
	v_mov_b32_e32 v135, 0
	v_mov_b32_e32 v136, 0
	v_mov_b32_e32 v137, 0
	v_mov_b32_e32 v130, 0
	v_mov_b32_e32 v131, 0
	v_mov_b32_e32 v132, 0
	v_mov_b32_e32 v133, 0
	s_cbranch_vccnz .LBB0_377
	global_load_dwordx4 v[134:137], v[198:199], off offset:512
	global_load_dwordx4 v[130:133], v[198:199], off offset:528
	s_waitcnt vmcnt(0)
.LBB0_377:
	v_pk_fma_f32 v[32:33], v[32:33], v[214:215], v[136:137]
	v_pk_fma_f32 v[30:31], v[30:31], v[196:197], v[134:135]
	v_pk_fma_f32 v[28:29], v[28:29], v[192:193], v[132:133]
	v_pk_fma_f32 v[26:27], v[26:27], v[186:187], v[130:131]
	s_and_b64 vcc, exec, s[4:5]
	global_store_dwordx4 v[204:205], v[30:33], off offset:512
	global_store_dwordx4 v[204:205], v[26:29], off offset:528
	s_cbranch_vccnz .LBB0_379
	v_pk_mul_f32 v[132:133], v[222:223], v[32:33]
	v_pk_mul_f32 v[130:131], v[220:221], v[30:31]
	v_pk_mul_f32 v[134:135], v[218:219], v[28:29]
	v_cvt_pk_bf16_f32 v130, v130, v131
	v_cvt_pk_bf16_f32 v131, v132, v133
	v_cvt_pk_bf16_f32 v133, v134, v135
	v_lshlrev_b64 v[134:135], 11, v[168:169]
	v_pk_mul_f32 v[136:137], v[216:217], v[26:27]
	v_lshl_add_u64 v[134:135], s[20:21], 0, v[134:135]
	v_cvt_pk_bf16_f32 v132, v136, v137
	v_lshl_add_u64 v[134:135], v[154:155], 1, v[134:135]
	global_store_dwordx4 v[134:135], v[130:133], off offset:256
.LBB0_379:
	v_mov_b32_e32 v134, 0
	s_and_b64 vcc, exec, s[6:7]
	v_mov_b32_e32 v135, 0
	v_mov_b32_e32 v136, 0
	v_mov_b32_e32 v137, 0
	v_mov_b32_e32 v130, 0
	v_mov_b32_e32 v131, 0
	v_mov_b32_e32 v132, 0
	v_mov_b32_e32 v133, 0
	s_cbranch_vccnz .LBB0_381
	global_load_dwordx4 v[134:137], v[202:203], off offset:512
	global_load_dwordx4 v[130:133], v[202:203], off offset:528
	s_waitcnt vmcnt(0)
.LBB0_381:
	v_pk_fma_f32 v[24:25], v[24:25], v[214:215], v[136:137]
	v_pk_fma_f32 v[22:23], v[22:23], v[196:197], v[134:135]
	v_pk_fma_f32 v[20:21], v[20:21], v[192:193], v[132:133]
	v_pk_fma_f32 v[18:19], v[18:19], v[186:187], v[130:131]
	s_and_b64 vcc, exec, s[4:5]
	global_store_dwordx4 v[208:209], v[22:25], off offset:512
	global_store_dwordx4 v[208:209], v[18:21], off offset:528
	s_cbranch_vccnz .LBB0_383
	v_pk_mul_f32 v[132:133], v[222:223], v[24:25]
	v_pk_mul_f32 v[130:131], v[220:221], v[22:23]
	v_pk_mul_f32 v[134:135], v[218:219], v[20:21]
	v_cvt_pk_bf16_f32 v130, v130, v131
	v_cvt_pk_bf16_f32 v131, v132, v133
	v_cvt_pk_bf16_f32 v133, v134, v135
	v_lshlrev_b64 v[134:135], 11, v[172:173]
	v_pk_mul_f32 v[136:137], v[216:217], v[18:19]
	v_lshl_add_u64 v[134:135], s[20:21], 0, v[134:135]
	v_cvt_pk_bf16_f32 v132, v136, v137
	v_lshl_add_u64 v[134:135], v[154:155], 1, v[134:135]
	global_store_dwordx4 v[134:135], v[130:133], off offset:256
.LBB0_383:
	v_mov_b32_e32 v134, 0
	s_and_b64 vcc, exec, s[6:7]
	v_mov_b32_e32 v135, 0
	v_mov_b32_e32 v136, 0
	v_mov_b32_e32 v137, 0
	v_mov_b32_e32 v130, 0
	v_mov_b32_e32 v131, 0
	v_mov_b32_e32 v132, 0
	v_mov_b32_e32 v133, 0
	s_cbranch_vccnz .LBB0_385
	global_load_dwordx4 v[134:137], v[206:207], off offset:512
	global_load_dwordx4 v[130:133], v[206:207], off offset:528
	s_waitcnt vmcnt(0)
.LBB0_385:
	v_pk_fma_f32 v[16:17], v[16:17], v[214:215], v[136:137]
	v_pk_fma_f32 v[14:15], v[14:15], v[196:197], v[134:135]
	v_pk_fma_f32 v[12:13], v[12:13], v[192:193], v[132:133]
	v_pk_fma_f32 v[10:11], v[10:11], v[186:187], v[130:131]
	s_and_b64 vcc, exec, s[4:5]
	global_store_dwordx4 v[212:213], v[14:17], off offset:512
	global_store_dwordx4 v[212:213], v[10:13], off offset:528
	s_cbranch_vccnz .LBB0_387
	v_pk_mul_f32 v[132:133], v[222:223], v[16:17]
	v_pk_mul_f32 v[130:131], v[220:221], v[14:15]
	v_pk_mul_f32 v[134:135], v[218:219], v[12:13]
	v_cvt_pk_bf16_f32 v130, v130, v131
	v_cvt_pk_bf16_f32 v131, v132, v133
	v_cvt_pk_bf16_f32 v133, v134, v135
	v_lshlrev_b64 v[134:135], 11, v[176:177]
	v_pk_mul_f32 v[136:137], v[216:217], v[10:11]
	v_lshl_add_u64 v[134:135], s[20:21], 0, v[134:135]
	v_cvt_pk_bf16_f32 v132, v136, v137
	v_lshl_add_u64 v[134:135], v[154:155], 1, v[134:135]
	global_store_dwordx4 v[134:135], v[130:133], off offset:256
.LBB0_387:
	v_mov_b32_e32 v134, 0
	s_and_b64 vcc, exec, s[6:7]
	v_mov_b32_e32 v135, 0
	v_mov_b32_e32 v136, 0
	v_mov_b32_e32 v137, 0
	v_mov_b32_e32 v130, 0
	v_mov_b32_e32 v131, 0
	v_mov_b32_e32 v132, 0
	v_mov_b32_e32 v133, 0
	s_cbranch_vccnz .LBB0_389
	global_load_dwordx4 v[134:137], v[210:211], off offset:512
	global_load_dwordx4 v[130:133], v[210:211], off offset:528
	s_waitcnt vmcnt(0)
.LBB0_389:
	v_pk_fma_f32 v[8:9], v[8:9], v[214:215], v[136:137]
	v_pk_fma_f32 v[6:7], v[6:7], v[196:197], v[134:135]
	v_pk_fma_f32 v[4:5], v[4:5], v[192:193], v[132:133]
	v_pk_fma_f32 v[2:3], v[2:3], v[186:187], v[130:131]
	s_and_b64 vcc, exec, s[4:5]
	global_store_dwordx4 v[182:183], v[6:9], off offset:512
	global_store_dwordx4 v[182:183], v[2:5], off offset:528
	s_cbranch_vccnz .LBB0_392
	v_pk_mul_f32 v[132:133], v[222:223], v[8:9]
	v_pk_mul_f32 v[130:131], v[220:221], v[6:7]
	v_pk_mul_f32 v[134:135], v[218:219], v[4:5]
	v_cvt_pk_bf16_f32 v130, v130, v131
	v_cvt_pk_bf16_f32 v131, v132, v133
	v_cvt_pk_bf16_f32 v133, v134, v135
	v_lshlrev_b64 v[134:135], 11, v[184:185]
	v_pk_mul_f32 v[136:137], v[216:217], v[2:3]
	v_lshl_add_u64 v[134:135], s[20:21], 0, v[134:135]
	v_cvt_pk_bf16_f32 v132, v136, v137
	v_lshl_add_u64 v[134:135], v[154:155], 1, v[134:135]
	global_store_dwordx4 v[134:135], v[130:133], off offset:256
	s_and_b64 vcc, exec, s[36:37]
	s_cbranch_vccnz .LBB0_393

.LBB0_1275:
	s_lshl_b32 s30, s6, 8
	s_add_i32 s21, s30, 0xffffc000
	s_and_b64 s[6:7], s[42:43], exec
	s_cselect_b32 s6, s21, s30
	v_add_u32_e32 v190, s6, v1
	v_ashrrev_i32_e32 v191, 31, v190
	v_lshlrev_b64 v[140:141], 10, v[190:191]
	v_lshl_add_u64 v[166:167], v[140:141], 0, v[162:163]
	v_cndmask_b32_e64 v139, 0, 1, s[34:35]
	v_cmp_ne_u32_e64 s[6:7], 1, v139
	s_andn2_b64 vcc, exec, s[34:35]
	v_lshl_add_u64 v[178:179], v[166:167], 2, s[40:41]
	v_mov_b32_e32 v139, 0
	v_mov_b32_e32 v140, 0
	v_mov_b32_e32 v141, 0
	v_mov_b32_e32 v142, 0
	v_mov_b32_e32 v143, 0
	v_mov_b32_e32 v144, 0
	v_mov_b32_e32 v145, 0
	s_cbranch_vccnz .LBB0_1277
	global_load_dwordx4 v[138:141], v[178:179], off
	global_load_dwordx4 v[142:145], v[178:179], off offset:16
	s_waitcnt vmcnt(0)
.LBB0_1277:
	v_add_u32_e32 v164, s30, v1
	v_pk_fma_f32 v[76:77], v[76:77], v[136:137], v[140:141]
	v_pk_fma_f32 v[74:75], v[74:75], v[134:135], v[138:139]
	v_pk_fma_f32 v[84:85], v[84:85], v[132:133], v[144:145]
	v_pk_fma_f32 v[82:83], v[82:83], v[130:131], v[142:143]
	v_lshl_add_u64 v[186:187], v[166:167], 2, s[38:39]
	s_and_b64 vcc, exec, s[4:5]
	v_ashrrev_i32_e32 v165, 31, v164
	global_store_dwordx4 v[186:187], v[74:77], off
	global_store_dwordx4 v[186:187], v[82:85], off offset:16
	s_cbranch_vccnz .LBB0_1279
	v_pk_mul_f32 v[140:141], v[222:223], v[76:77]
	v_pk_mul_f32 v[138:139], v[220:221], v[74:75]
	v_pk_mul_f32 v[142:143], v[218:219], v[84:85]
	v_cvt_pk_bf16_f32 v138, v138, v139
	v_cvt_pk_bf16_f32 v139, v140, v141
	v_cvt_pk_bf16_f32 v141, v142, v143
	v_lshlrev_b64 v[142:143], 11, v[164:165]
	v_pk_mul_f32 v[144:145], v[216:217], v[82:83]
	v_lshl_add_u64 v[142:143], s[14:15], 0, v[142:143]
	v_cvt_pk_bf16_f32 v140, v144, v145
	v_lshl_add_u64 v[142:143], v[162:163], 1, v[142:143]
	global_store_dwordx4 v[142:143], v[138:141], off
.LBB0_1279:
	s_nop 1
	v_or_b32_e32 v138, 16, v190
	v_ashrrev_i32_e32 v139, 31, v138
	v_lshlrev_b64 v[138:139], 10, v[138:139]
	v_lshl_add_u64 v[168:169], v[138:139], 0, v[162:163]
	v_mov_b32_e32 v142, 0
	s_and_b64 vcc, exec, s[6:7]
	v_lshl_add_u64 v[182:183], v[168:169], 2, s[40:41]
	v_mov_b32_e32 v143, 0
	v_mov_b32_e32 v144, 0
	v_mov_b32_e32 v145, 0
	v_mov_b32_e32 v138, 0
	v_mov_b32_e32 v139, 0
	v_mov_b32_e32 v140, 0
	v_mov_b32_e32 v141, 0
	s_cbranch_vccnz .LBB0_1281
	global_load_dwordx4 v[142:145], v[182:183], off
	global_load_dwordx4 v[138:141], v[182:183], off offset:16
	s_waitcnt vmcnt(0)
.LBB0_1281:
	v_add_u32_e32 v166, s30, v237
	v_pk_fma_f32 v[92:93], v[92:93], v[136:137], v[144:145]
	v_pk_fma_f32 v[90:91], v[90:91], v[134:135], v[142:143]
	v_pk_fma_f32 v[96:97], v[96:97], v[132:133], v[140:141]
	v_pk_fma_f32 v[94:95], v[94:95], v[130:131], v[138:139]
	v_lshl_add_u64 v[192:193], v[168:169], 2, s[38:39]
	s_and_b64 vcc, exec, s[4:5]
	v_ashrrev_i32_e32 v167, 31, v166
	global_store_dwordx4 v[192:193], v[90:93], off
	global_store_dwordx4 v[192:193], v[94:97], off offset:16
	s_cbranch_vccnz .LBB0_1283
	v_pk_mul_f32 v[140:141], v[222:223], v[92:93]
	v_pk_mul_f32 v[138:139], v[220:221], v[90:91]
	v_pk_mul_f32 v[142:143], v[218:219], v[96:97]
	v_cvt_pk_bf16_f32 v138, v138, v139
	v_cvt_pk_bf16_f32 v139, v140, v141
	v_cvt_pk_bf16_f32 v141, v142, v143
	v_lshlrev_b64 v[142:143], 11, v[166:167]
	v_pk_mul_f32 v[144:145], v[216:217], v[94:95]
	v_lshl_add_u64 v[142:143], s[14:15], 0, v[142:143]
	v_cvt_pk_bf16_f32 v140, v144, v145
	v_lshl_add_u64 v[142:143], v[162:163], 1, v[142:143]
	global_store_dwordx4 v[142:143], v[138:141], off
.LBB0_1283:
	s_nop 1
	v_or_b32_e32 v138, 32, v190
	v_ashrrev_i32_e32 v139, 31, v138
	v_lshlrev_b64 v[138:139], 10, v[138:139]
	v_lshl_add_u64 v[174:175], v[138:139], 0, v[162:163]
	v_mov_b32_e32 v142, 0
	s_and_b64 vcc, exec, s[6:7]
	v_lshl_add_u64 v[188:189], v[174:175], 2, s[40:41]
	v_mov_b32_e32 v143, 0
	v_mov_b32_e32 v144, 0
	v_mov_b32_e32 v145, 0
	v_mov_b32_e32 v138, 0
	v_mov_b32_e32 v139, 0
	v_mov_b32_e32 v140, 0
	v_mov_b32_e32 v141, 0
	s_cbranch_vccnz .LBB0_1285
	global_load_dwordx4 v[142:145], v[188:189], off
	global_load_dwordx4 v[138:141], v[188:189], off offset:16
	s_waitcnt vmcnt(0)
.LBB0_1285:
	v_add_u32_e32 v168, s30, v238
	v_pk_fma_f32 v[100:101], v[100:101], v[136:137], v[144:145]
	v_pk_fma_f32 v[98:99], v[98:99], v[134:135], v[142:143]
	v_pk_fma_f32 v[104:105], v[104:105], v[132:133], v[140:141]
	v_pk_fma_f32 v[102:103], v[102:103], v[130:131], v[138:139]
	v_lshl_add_u64 v[196:197], v[174:175], 2, s[38:39]
	s_and_b64 vcc, exec, s[4:5]
	v_ashrrev_i32_e32 v169, 31, v168
	global_store_dwordx4 v[196:197], v[98:101], off
	global_store_dwordx4 v[196:197], v[102:105], off offset:16
	s_cbranch_vccnz .LBB0_1287
	v_pk_mul_f32 v[140:141], v[222:223], v[100:101]
	v_pk_mul_f32 v[138:139], v[220:221], v[98:99]
	v_pk_mul_f32 v[142:143], v[218:219], v[104:105]
	v_cvt_pk_bf16_f32 v138, v138, v139
	v_cvt_pk_bf16_f32 v139, v140, v141
	v_cvt_pk_bf16_f32 v141, v142, v143
	v_lshlrev_b64 v[142:143], 11, v[168:169]
	v_pk_mul_f32 v[144:145], v[216:217], v[102:103]
	v_lshl_add_u64 v[142:143], s[14:15], 0, v[142:143]
	v_cvt_pk_bf16_f32 v140, v144, v145
	v_lshl_add_u64 v[142:143], v[162:163], 1, v[142:143]
	global_store_dwordx4 v[142:143], v[138:141], off
.LBB0_1287:
	s_nop 1
	v_or_b32_e32 v138, 48, v190
	v_ashrrev_i32_e32 v139, 31, v138
	v_lshlrev_b64 v[138:139], 10, v[138:139]
	v_lshl_add_u64 v[176:177], v[138:139], 0, v[162:163]
	v_mov_b32_e32 v142, 0
	s_and_b64 vcc, exec, s[6:7]
	v_lshl_add_u64 v[194:195], v[176:177], 2, s[40:41]
	v_mov_b32_e32 v143, 0
	v_mov_b32_e32 v144, 0
	v_mov_b32_e32 v145, 0
	v_mov_b32_e32 v138, 0
	v_mov_b32_e32 v139, 0
	v_mov_b32_e32 v140, 0
	v_mov_b32_e32 v141, 0
	s_cbranch_vccnz .LBB0_1289
	global_load_dwordx4 v[142:145], v[194:195], off
	global_load_dwordx4 v[138:141], v[194:195], off offset:16
	s_waitcnt vmcnt(0)
.LBB0_1289:
	v_add_u32_e32 v174, s30, v239
	v_pk_fma_f32 v[116:117], v[116:117], v[136:137], v[144:145]
	v_pk_fma_f32 v[114:115], v[114:115], v[134:135], v[142:143]
	v_pk_fma_f32 v[120:121], v[120:121], v[132:133], v[140:141]
	v_pk_fma_f32 v[118:119], v[118:119], v[130:131], v[138:139]
	v_lshl_add_u64 v[200:201], v[176:177], 2, s[38:39]
	s_and_b64 vcc, exec, s[4:5]
	v_ashrrev_i32_e32 v175, 31, v174
	global_store_dwordx4 v[200:201], v[114:117], off
	global_store_dwordx4 v[200:201], v[118:121], off offset:16
	s_cbranch_vccnz .LBB0_1291
	v_pk_mul_f32 v[140:141], v[222:223], v[116:117]
	v_pk_mul_f32 v[138:139], v[220:221], v[114:115]
	v_pk_mul_f32 v[142:143], v[218:219], v[120:121]
	v_cvt_pk_bf16_f32 v138, v138, v139
	v_cvt_pk_bf16_f32 v139, v140, v141
	v_cvt_pk_bf16_f32 v141, v142, v143
	v_lshlrev_b64 v[142:143], 11, v[174:175]
	v_pk_mul_f32 v[144:145], v[216:217], v[118:119]
	v_lshl_add_u64 v[142:143], s[14:15], 0, v[142:143]
	v_cvt_pk_bf16_f32 v140, v144, v145
	v_lshl_add_u64 v[142:143], v[162:163], 1, v[142:143]
	global_store_dwordx4 v[142:143], v[138:141], off
.LBB0_1291:
	s_nop 1
	v_add_u32_e32 v138, 0x80, v190
	v_ashrrev_i32_e32 v139, 31, v138
	v_lshlrev_b64 v[138:139], 10, v[138:139]
	v_lshl_add_u64 v[180:181], v[138:139], 0, v[162:163]
	v_mov_b32_e32 v142, 0
	s_and_b64 vcc, exec, s[6:7]
	v_lshl_add_u64 v[198:199], v[180:181], 2, s[40:41]
	v_mov_b32_e32 v143, 0
	v_mov_b32_e32 v144, 0
	v_mov_b32_e32 v145, 0
	v_mov_b32_e32 v138, 0
	v_mov_b32_e32 v139, 0
	v_mov_b32_e32 v140, 0
	v_mov_b32_e32 v141, 0
	s_cbranch_vccnz .LBB0_1293
	global_load_dwordx4 v[142:145], v[198:199], off
	global_load_dwordx4 v[138:141], v[198:199], off offset:16
	s_waitcnt vmcnt(0)
.LBB0_1293:
	v_add_u32_e32 v176, s30, v240
	v_pk_fma_f32 v[124:125], v[124:125], v[136:137], v[144:145]
	v_pk_fma_f32 v[122:123], v[122:123], v[134:135], v[142:143]
	v_pk_fma_f32 v[128:129], v[128:129], v[132:133], v[140:141]
	v_pk_fma_f32 v[126:127], v[126:127], v[130:131], v[138:139]
	v_lshl_add_u64 v[204:205], v[180:181], 2, s[38:39]
	s_and_b64 vcc, exec, s[4:5]
	v_ashrrev_i32_e32 v177, 31, v176
	global_store_dwordx4 v[204:205], v[122:125], off
	global_store_dwordx4 v[204:205], v[126:129], off offset:16
	s_cbranch_vccnz .LBB0_1295
	v_pk_mul_f32 v[140:141], v[222:223], v[124:125]
	v_pk_mul_f32 v[138:139], v[220:221], v[122:123]
	v_pk_mul_f32 v[142:143], v[218:219], v[128:129]
	v_cvt_pk_bf16_f32 v138, v138, v139
	v_cvt_pk_bf16_f32 v139, v140, v141
	v_cvt_pk_bf16_f32 v141, v142, v143
	v_lshlrev_b64 v[142:143], 11, v[176:177]
	v_pk_mul_f32 v[144:145], v[216:217], v[126:127]
	v_lshl_add_u64 v[142:143], s[14:15], 0, v[142:143]
	v_cvt_pk_bf16_f32 v140, v144, v145
	v_lshl_add_u64 v[142:143], v[162:163], 1, v[142:143]
	global_store_dwordx4 v[142:143], v[138:141], off
.LBB0_1295:
	s_nop 1
	v_add_u32_e32 v138, 0x90, v190
	v_ashrrev_i32_e32 v139, 31, v138
	v_lshlrev_b64 v[138:139], 10, v[138:139]
	v_lshl_add_u64 v[184:185], v[138:139], 0, v[162:163]
	v_mov_b32_e32 v142, 0
	s_and_b64 vcc, exec, s[6:7]
	v_lshl_add_u64 v[202:203], v[184:185], 2, s[40:41]
	v_mov_b32_e32 v143, 0
	v_mov_b32_e32 v144, 0
	v_mov_b32_e32 v145, 0
	v_mov_b32_e32 v138, 0
	v_mov_b32_e32 v139, 0
	v_mov_b32_e32 v140, 0
	v_mov_b32_e32 v141, 0
	s_cbranch_vccnz .LBB0_1297
	global_load_dwordx4 v[142:145], v[202:203], off
	global_load_dwordx4 v[138:141], v[202:203], off offset:16
	s_waitcnt vmcnt(0)
.LBB0_1297:
	v_add_u32_e32 v180, s30, v241
	v_pk_fma_f32 v[112:113], v[112:113], v[136:137], v[144:145]
	v_pk_fma_f32 v[110:111], v[110:111], v[134:135], v[142:143]
	v_pk_fma_f32 v[108:109], v[108:109], v[132:133], v[140:141]
	v_pk_fma_f32 v[106:107], v[106:107], v[130:131], v[138:139]
	v_lshl_add_u64 v[208:209], v[184:185], 2, s[38:39]
	s_and_b64 vcc, exec, s[4:5]
	v_ashrrev_i32_e32 v181, 31, v180
	global_store_dwordx4 v[208:209], v[110:113], off
	global_store_dwordx4 v[208:209], v[106:109], off offset:16
	s_cbranch_vccnz .LBB0_1299
	v_pk_mul_f32 v[140:141], v[222:223], v[112:113]
	v_pk_mul_f32 v[138:139], v[220:221], v[110:111]
	v_pk_mul_f32 v[142:143], v[218:219], v[108:109]
	v_cvt_pk_bf16_f32 v138, v138, v139
	v_cvt_pk_bf16_f32 v139, v140, v141
	v_cvt_pk_bf16_f32 v141, v142, v143
	v_lshlrev_b64 v[142:143], 11, v[180:181]
	v_pk_mul_f32 v[144:145], v[216:217], v[106:107]
	v_lshl_add_u64 v[142:143], s[14:15], 0, v[142:143]
	v_cvt_pk_bf16_f32 v140, v144, v145
	v_lshl_add_u64 v[142:143], v[162:163], 1, v[142:143]
	global_store_dwordx4 v[142:143], v[138:141], off
.LBB0_1299:
	s_nop 1
	v_add_u32_e32 v138, 0xa0, v190
	v_ashrrev_i32_e32 v139, 31, v138
	v_lshlrev_b64 v[138:139], 10, v[138:139]
	v_lshl_add_u64 v[210:211], v[138:139], 0, v[162:163]
	v_mov_b32_e32 v142, 0
	s_and_b64 vcc, exec, s[6:7]
	v_lshl_add_u64 v[206:207], v[210:211], 2, s[40:41]
	v_mov_b32_e32 v143, 0
	v_mov_b32_e32 v144, 0
	v_mov_b32_e32 v145, 0
	v_mov_b32_e32 v138, 0
	v_mov_b32_e32 v139, 0
	v_mov_b32_e32 v140, 0
	v_mov_b32_e32 v141, 0
	s_cbranch_vccnz .LBB0_1301
	global_load_dwordx4 v[142:145], v[206:207], off
	global_load_dwordx4 v[138:141], v[206:207], off offset:16
	s_waitcnt vmcnt(0)
.LBB0_1301:
	v_add_u32_e32 v184, s30, v242
	v_pk_fma_f32 v[88:89], v[88:89], v[136:137], v[144:145]
	v_pk_fma_f32 v[86:87], v[86:87], v[134:135], v[142:143]
	v_pk_fma_f32 v[80:81], v[80:81], v[132:133], v[140:141]
	v_pk_fma_f32 v[78:79], v[78:79], v[130:131], v[138:139]
	v_lshl_add_u64 v[212:213], v[210:211], 2, s[38:39]
	s_and_b64 vcc, exec, s[4:5]
	v_ashrrev_i32_e32 v185, 31, v184
	global_store_dwordx4 v[212:213], v[86:89], off
	global_store_dwordx4 v[212:213], v[78:81], off offset:16
	s_cbranch_vccnz .LBB0_1303
	v_pk_mul_f32 v[140:141], v[222:223], v[88:89]
	v_pk_mul_f32 v[138:139], v[220:221], v[86:87]
	v_pk_mul_f32 v[142:143], v[218:219], v[80:81]
	v_cvt_pk_bf16_f32 v138, v138, v139
	v_cvt_pk_bf16_f32 v139, v140, v141
	v_cvt_pk_bf16_f32 v141, v142, v143
	v_lshlrev_b64 v[142:143], 11, v[184:185]
	v_pk_mul_f32 v[144:145], v[216:217], v[78:79]
	v_lshl_add_u64 v[142:143], s[14:15], 0, v[142:143]
	v_cvt_pk_bf16_f32 v140, v144, v145
	v_lshl_add_u64 v[142:143], v[162:163], 1, v[142:143]
	global_store_dwordx4 v[142:143], v[138:141], off
.LBB0_1303:
	s_nop 1
	v_add_u32_e32 v138, 0xb0, v190
	v_ashrrev_i32_e32 v139, 31, v138
	v_lshlrev_b64 v[138:139], 10, v[138:139]
	v_lshl_add_u64 v[214:215], v[138:139], 0, v[162:163]
	v_mov_b32_e32 v142, 0
	s_and_b64 vcc, exec, s[6:7]
	v_lshl_add_u64 v[210:211], v[214:215], 2, s[40:41]
	v_mov_b32_e32 v143, 0
	v_mov_b32_e32 v144, 0
	v_mov_b32_e32 v145, 0
	v_mov_b32_e32 v138, 0
	v_mov_b32_e32 v139, 0
	v_mov_b32_e32 v140, 0
	v_mov_b32_e32 v141, 0
	s_cbranch_vccnz .LBB0_1305
	global_load_dwordx4 v[142:145], v[210:211], off
	global_load_dwordx4 v[138:141], v[210:211], off offset:16
	s_waitcnt vmcnt(0)
.LBB0_1305:
	v_add_u32_e32 v190, s30, v243
	v_pk_fma_f32 v[72:73], v[72:73], v[136:137], v[144:145]
	v_pk_fma_f32 v[70:71], v[70:71], v[134:135], v[142:143]
	v_pk_fma_f32 v[68:69], v[68:69], v[132:133], v[140:141]
	v_pk_fma_f32 v[66:67], v[66:67], v[130:131], v[138:139]
	v_lshl_add_u64 v[214:215], v[214:215], 2, s[38:39]
	s_and_b64 vcc, exec, s[4:5]
	v_ashrrev_i32_e32 v191, 31, v190
	global_store_dwordx4 v[214:215], v[70:73], off
	global_store_dwordx4 v[214:215], v[66:69], off offset:16
	s_cbranch_vccnz .LBB0_1307
	v_pk_mul_f32 v[132:133], v[222:223], v[72:73]
	v_pk_mul_f32 v[130:131], v[220:221], v[70:71]
	v_pk_mul_f32 v[134:135], v[218:219], v[68:69]
	v_cvt_pk_bf16_f32 v130, v130, v131
	v_cvt_pk_bf16_f32 v131, v132, v133
	v_cvt_pk_bf16_f32 v133, v134, v135
	v_lshlrev_b64 v[134:135], 11, v[190:191]
	v_pk_mul_f32 v[136:137], v[216:217], v[66:67]
	v_lshl_add_u64 v[134:135], s[14:15], 0, v[134:135]
	v_cvt_pk_bf16_f32 v132, v136, v137
	v_lshl_add_u64 v[134:135], v[162:163], 1, v[134:135]
	global_store_dwordx4 v[134:135], v[130:133], off

.LBB0_1311:
	s_and_b64 vcc, exec, s[6:7]
	v_mov_b32_e32 v139, 0
	v_mov_b32_e32 v140, 0
	v_mov_b32_e32 v141, 0
	v_mov_b32_e32 v142, 0
	v_mov_b32_e32 v143, 0
	v_mov_b32_e32 v144, 0
	v_mov_b32_e32 v145, 0
	s_cbranch_vccnz .LBB0_1313
	global_load_dwordx4 v[138:141], v[178:179], off offset:512
	global_load_dwordx4 v[142:145], v[178:179], off offset:528
	s_waitcnt vmcnt(0)
.LBB0_1313:
	v_pk_fma_f32 v[64:65], v[64:65], v[136:137], v[140:141]
	v_pk_fma_f32 v[62:63], v[62:63], v[134:135], v[138:139]
	v_pk_fma_f32 v[60:61], v[60:61], v[132:133], v[144:145]
	v_pk_fma_f32 v[58:59], v[58:59], v[130:131], v[142:143]
	s_and_b64 vcc, exec, s[4:5]
	global_store_dwordx4 v[186:187], v[62:65], off offset:512
	global_store_dwordx4 v[186:187], v[58:61], off offset:528
	s_cbranch_vccnz .LBB0_1315
	v_pk_mul_f32 v[140:141], v[222:223], v[64:65]
	v_pk_mul_f32 v[138:139], v[220:221], v[62:63]
	v_pk_mul_f32 v[142:143], v[218:219], v[60:61]
	v_cvt_pk_bf16_f32 v138, v138, v139
	v_cvt_pk_bf16_f32 v139, v140, v141
	v_cvt_pk_bf16_f32 v141, v142, v143
	v_lshlrev_b64 v[142:143], 11, v[164:165]
	v_pk_mul_f32 v[144:145], v[216:217], v[58:59]
	v_lshl_add_u64 v[142:143], s[14:15], 0, v[142:143]
	v_cvt_pk_bf16_f32 v140, v144, v145
	v_lshl_add_u64 v[142:143], v[162:163], 1, v[142:143]
	global_store_dwordx4 v[142:143], v[138:141], off offset:256
.LBB0_1315:
	v_mov_b32_e32 v142, 0
	s_and_b64 vcc, exec, s[6:7]
	v_mov_b32_e32 v143, 0
	v_mov_b32_e32 v144, 0
	v_mov_b32_e32 v145, 0
	v_mov_b32_e32 v138, 0
	v_mov_b32_e32 v139, 0
	v_mov_b32_e32 v140, 0
	v_mov_b32_e32 v141, 0
	s_cbranch_vccnz .LBB0_1317
	global_load_dwordx4 v[142:145], v[182:183], off offset:512
	global_load_dwordx4 v[138:141], v[182:183], off offset:528
	s_waitcnt vmcnt(0)
.LBB0_1317:
	v_pk_fma_f32 v[56:57], v[56:57], v[136:137], v[144:145]
	v_pk_fma_f32 v[54:55], v[54:55], v[134:135], v[142:143]
	v_pk_fma_f32 v[52:53], v[52:53], v[132:133], v[140:141]
	v_pk_fma_f32 v[50:51], v[50:51], v[130:131], v[138:139]
	s_and_b64 vcc, exec, s[4:5]
	global_store_dwordx4 v[192:193], v[54:57], off offset:512
	global_store_dwordx4 v[192:193], v[50:53], off offset:528
	s_cbranch_vccnz .LBB0_1319
	v_pk_mul_f32 v[140:141], v[222:223], v[56:57]
	v_pk_mul_f32 v[138:139], v[220:221], v[54:55]
	v_pk_mul_f32 v[142:143], v[218:219], v[52:53]
	v_cvt_pk_bf16_f32 v138, v138, v139
	v_cvt_pk_bf16_f32 v139, v140, v141
	v_cvt_pk_bf16_f32 v141, v142, v143
	v_lshlrev_b64 v[142:143], 11, v[166:167]
	v_pk_mul_f32 v[144:145], v[216:217], v[50:51]
	v_lshl_add_u64 v[142:143], s[14:15], 0, v[142:143]
	v_cvt_pk_bf16_f32 v140, v144, v145
	v_lshl_add_u64 v[142:143], v[162:163], 1, v[142:143]
	global_store_dwordx4 v[142:143], v[138:141], off offset:256
.LBB0_1319:
	v_mov_b32_e32 v142, 0
	s_and_b64 vcc, exec, s[6:7]
	v_mov_b32_e32 v143, 0
	v_mov_b32_e32 v144, 0
	v_mov_b32_e32 v145, 0
	v_mov_b32_e32 v138, 0
	v_mov_b32_e32 v139, 0
	v_mov_b32_e32 v140, 0
	v_mov_b32_e32 v141, 0
	s_cbranch_vccnz .LBB0_1321
	global_load_dwordx4 v[142:145], v[188:189], off offset:512
	global_load_dwordx4 v[138:141], v[188:189], off offset:528
	s_waitcnt vmcnt(0)
.LBB0_1321:
	v_pk_fma_f32 v[48:49], v[48:49], v[136:137], v[144:145]
	v_pk_fma_f32 v[46:47], v[46:47], v[134:135], v[142:143]
	v_pk_fma_f32 v[44:45], v[44:45], v[132:133], v[140:141]
	v_pk_fma_f32 v[42:43], v[42:43], v[130:131], v[138:139]
	s_and_b64 vcc, exec, s[4:5]
	global_store_dwordx4 v[196:197], v[46:49], off offset:512
	global_store_dwordx4 v[196:197], v[42:45], off offset:528
	s_cbranch_vccnz .LBB0_1323
	v_pk_mul_f32 v[140:141], v[222:223], v[48:49]
	v_pk_mul_f32 v[138:139], v[220:221], v[46:47]
	v_pk_mul_f32 v[142:143], v[218:219], v[44:45]
	v_cvt_pk_bf16_f32 v138, v138, v139
	v_cvt_pk_bf16_f32 v139, v140, v141
	v_cvt_pk_bf16_f32 v141, v142, v143
	v_lshlrev_b64 v[142:143], 11, v[168:169]
	v_pk_mul_f32 v[144:145], v[216:217], v[42:43]
	v_lshl_add_u64 v[142:143], s[14:15], 0, v[142:143]
	v_cvt_pk_bf16_f32 v140, v144, v145
	v_lshl_add_u64 v[142:143], v[162:163], 1, v[142:143]
	global_store_dwordx4 v[142:143], v[138:141], off offset:256
.LBB0_1323:
	v_mov_b32_e32 v142, 0
	s_and_b64 vcc, exec, s[6:7]
	v_mov_b32_e32 v143, 0
	v_mov_b32_e32 v144, 0
	v_mov_b32_e32 v145, 0
	v_mov_b32_e32 v138, 0
	v_mov_b32_e32 v139, 0
	v_mov_b32_e32 v140, 0
	v_mov_b32_e32 v141, 0
	s_cbranch_vccnz .LBB0_1325
	global_load_dwordx4 v[142:145], v[194:195], off offset:512
	global_load_dwordx4 v[138:141], v[194:195], off offset:528
	s_waitcnt vmcnt(0)
.LBB0_1325:
	v_pk_fma_f32 v[40:41], v[40:41], v[136:137], v[144:145]
	v_pk_fma_f32 v[38:39], v[38:39], v[134:135], v[142:143]
	v_pk_fma_f32 v[36:37], v[36:37], v[132:133], v[140:141]
	v_pk_fma_f32 v[34:35], v[34:35], v[130:131], v[138:139]
	s_and_b64 vcc, exec, s[4:5]
	global_store_dwordx4 v[200:201], v[38:41], off offset:512
	global_store_dwordx4 v[200:201], v[34:37], off offset:528
	s_cbranch_vccnz .LBB0_1327
	v_pk_mul_f32 v[140:141], v[222:223], v[40:41]
	v_pk_mul_f32 v[138:139], v[220:221], v[38:39]
	v_pk_mul_f32 v[142:143], v[218:219], v[36:37]
	v_cvt_pk_bf16_f32 v138, v138, v139
	v_cvt_pk_bf16_f32 v139, v140, v141
	v_cvt_pk_bf16_f32 v141, v142, v143
	v_lshlrev_b64 v[142:143], 11, v[174:175]
	v_pk_mul_f32 v[144:145], v[216:217], v[34:35]
	v_lshl_add_u64 v[142:143], s[14:15], 0, v[142:143]
	v_cvt_pk_bf16_f32 v140, v144, v145
	v_lshl_add_u64 v[142:143], v[162:163], 1, v[142:143]
	global_store_dwordx4 v[142:143], v[138:141], off offset:256
.LBB0_1327:
	v_mov_b32_e32 v142, 0
	s_and_b64 vcc, exec, s[6:7]
	v_mov_b32_e32 v143, 0
	v_mov_b32_e32 v144, 0
	v_mov_b32_e32 v145, 0
	v_mov_b32_e32 v138, 0
	v_mov_b32_e32 v139, 0
	v_mov_b32_e32 v140, 0
	v_mov_b32_e32 v141, 0
	s_cbranch_vccnz .LBB0_1329
	global_load_dwordx4 v[142:145], v[198:199], off offset:512
	global_load_dwordx4 v[138:141], v[198:199], off offset:528
	s_waitcnt vmcnt(0)
.LBB0_1329:
	v_pk_fma_f32 v[32:33], v[32:33], v[136:137], v[144:145]
	v_pk_fma_f32 v[30:31], v[30:31], v[134:135], v[142:143]
	v_pk_fma_f32 v[28:29], v[28:29], v[132:133], v[140:141]
	v_pk_fma_f32 v[26:27], v[26:27], v[130:131], v[138:139]
	s_and_b64 vcc, exec, s[4:5]
	global_store_dwordx4 v[204:205], v[30:33], off offset:512
	global_store_dwordx4 v[204:205], v[26:29], off offset:528
	s_cbranch_vccnz .LBB0_1331
	v_pk_mul_f32 v[140:141], v[222:223], v[32:33]
	v_pk_mul_f32 v[138:139], v[220:221], v[30:31]
	v_pk_mul_f32 v[142:143], v[218:219], v[28:29]
	v_cvt_pk_bf16_f32 v138, v138, v139
	v_cvt_pk_bf16_f32 v139, v140, v141
	v_cvt_pk_bf16_f32 v141, v142, v143
	v_lshlrev_b64 v[142:143], 11, v[176:177]
	v_pk_mul_f32 v[144:145], v[216:217], v[26:27]
	v_lshl_add_u64 v[142:143], s[14:15], 0, v[142:143]
	v_cvt_pk_bf16_f32 v140, v144, v145
	v_lshl_add_u64 v[142:143], v[162:163], 1, v[142:143]
	global_store_dwordx4 v[142:143], v[138:141], off offset:256
.LBB0_1331:
	v_mov_b32_e32 v142, 0
	s_and_b64 vcc, exec, s[6:7]
	v_mov_b32_e32 v143, 0
	v_mov_b32_e32 v144, 0
	v_mov_b32_e32 v145, 0
	v_mov_b32_e32 v138, 0
	v_mov_b32_e32 v139, 0
	v_mov_b32_e32 v140, 0
	v_mov_b32_e32 v141, 0
	s_cbranch_vccnz .LBB0_1333
	global_load_dwordx4 v[142:145], v[202:203], off offset:512
	global_load_dwordx4 v[138:141], v[202:203], off offset:528
	s_waitcnt vmcnt(0)
.LBB0_1333:
	v_pk_fma_f32 v[24:25], v[24:25], v[136:137], v[144:145]
	v_pk_fma_f32 v[22:23], v[22:23], v[134:135], v[142:143]
	v_pk_fma_f32 v[20:21], v[20:21], v[132:133], v[140:141]
	v_pk_fma_f32 v[18:19], v[18:19], v[130:131], v[138:139]
	s_and_b64 vcc, exec, s[4:5]
	global_store_dwordx4 v[208:209], v[22:25], off offset:512
	global_store_dwordx4 v[208:209], v[18:21], off offset:528
	s_cbranch_vccnz .LBB0_1335
	v_pk_mul_f32 v[140:141], v[222:223], v[24:25]
	v_pk_mul_f32 v[138:139], v[220:221], v[22:23]
	v_pk_mul_f32 v[142:143], v[218:219], v[20:21]
	v_cvt_pk_bf16_f32 v138, v138, v139
	v_cvt_pk_bf16_f32 v139, v140, v141
	v_cvt_pk_bf16_f32 v141, v142, v143
	v_lshlrev_b64 v[142:143], 11, v[180:181]
	v_pk_mul_f32 v[144:145], v[216:217], v[18:19]
	v_lshl_add_u64 v[142:143], s[14:15], 0, v[142:143]
	v_cvt_pk_bf16_f32 v140, v144, v145
	v_lshl_add_u64 v[142:143], v[162:163], 1, v[142:143]
	global_store_dwordx4 v[142:143], v[138:141], off offset:256
.LBB0_1335:
	v_mov_b32_e32 v142, 0
	s_and_b64 vcc, exec, s[6:7]
	v_mov_b32_e32 v143, 0
	v_mov_b32_e32 v144, 0
	v_mov_b32_e32 v145, 0
	v_mov_b32_e32 v138, 0
	v_mov_b32_e32 v139, 0
	v_mov_b32_e32 v140, 0
	v_mov_b32_e32 v141, 0
	s_cbranch_vccnz .LBB0_1337
	global_load_dwordx4 v[142:145], v[206:207], off offset:512
	global_load_dwordx4 v[138:141], v[206:207], off offset:528
	s_waitcnt vmcnt(0)
.LBB0_1337:
	v_pk_fma_f32 v[16:17], v[16:17], v[136:137], v[144:145]
	v_pk_fma_f32 v[14:15], v[14:15], v[134:135], v[142:143]
	v_pk_fma_f32 v[12:13], v[12:13], v[132:133], v[140:141]
	v_pk_fma_f32 v[10:11], v[10:11], v[130:131], v[138:139]
	s_and_b64 vcc, exec, s[4:5]
	global_store_dwordx4 v[212:213], v[14:17], off offset:512
	global_store_dwordx4 v[212:213], v[10:13], off offset:528
	s_cbranch_vccnz .LBB0_1339
	v_pk_mul_f32 v[140:141], v[222:223], v[16:17]
	v_pk_mul_f32 v[138:139], v[220:221], v[14:15]
	v_pk_mul_f32 v[142:143], v[218:219], v[12:13]
	v_cvt_pk_bf16_f32 v138, v138, v139
	v_cvt_pk_bf16_f32 v139, v140, v141
	v_cvt_pk_bf16_f32 v141, v142, v143
	v_lshlrev_b64 v[142:143], 11, v[184:185]
	v_pk_mul_f32 v[144:145], v[216:217], v[10:11]
	v_lshl_add_u64 v[142:143], s[14:15], 0, v[142:143]
	v_cvt_pk_bf16_f32 v140, v144, v145
	v_lshl_add_u64 v[142:143], v[162:163], 1, v[142:143]
	global_store_dwordx4 v[142:143], v[138:141], off offset:256
.LBB0_1339:
	v_mov_b32_e32 v142, 0
	s_and_b64 vcc, exec, s[6:7]
	v_mov_b32_e32 v143, 0
	v_mov_b32_e32 v144, 0
	v_mov_b32_e32 v145, 0
	v_mov_b32_e32 v138, 0
	v_mov_b32_e32 v139, 0
	v_mov_b32_e32 v140, 0
	v_mov_b32_e32 v141, 0
	s_cbranch_vccnz .LBB0_1341
	global_load_dwordx4 v[142:145], v[210:211], off offset:512
	global_load_dwordx4 v[138:141], v[210:211], off offset:528
	s_waitcnt vmcnt(0)
.LBB0_1341:
	v_pk_fma_f32 v[8:9], v[8:9], v[136:137], v[144:145]
	v_pk_fma_f32 v[6:7], v[6:7], v[134:135], v[142:143]
	v_pk_fma_f32 v[4:5], v[4:5], v[132:133], v[140:141]
	v_pk_fma_f32 v[2:3], v[2:3], v[130:131], v[138:139]
	s_and_b64 vcc, exec, s[4:5]
	global_store_dwordx4 v[214:215], v[6:9], off offset:512
	global_store_dwordx4 v[214:215], v[2:5], off offset:528
	s_cbranch_vccnz .LBB0_1344
	v_pk_mul_f32 v[132:133], v[222:223], v[8:9]
	v_pk_mul_f32 v[130:131], v[220:221], v[6:7]
	v_pk_mul_f32 v[134:135], v[218:219], v[4:5]
	v_cvt_pk_bf16_f32 v130, v130, v131
	v_cvt_pk_bf16_f32 v131, v132, v133
	v_cvt_pk_bf16_f32 v133, v134, v135
	v_lshlrev_b64 v[134:135], 11, v[190:191]
	v_pk_mul_f32 v[136:137], v[216:217], v[2:3]
	v_lshl_add_u64 v[134:135], s[14:15], 0, v[134:135]
	v_cvt_pk_bf16_f32 v132, v136, v137
	v_lshl_add_u64 v[134:135], v[162:163], 1, v[134:135]
	global_store_dwordx4 v[134:135], v[130:133], off offset:256
	s_and_b64 vcc, exec, s[34:35]
	s_cbranch_vccnz .LBB0_1345

.LBB0_1581:
	s_lshl_b32 s28, s67, 8
	s_add_i32 s23, s28, 0xffffc000
	s_and_b64 s[6:7], s[40:41], exec
	s_cselect_b32 s6, s23, s28
	v_add_u32_e32 v184, s6, v1
	v_ashrrev_i32_e32 v185, 31, v184
	v_lshlrev_b64 v[132:133], 10, v[184:185]
	v_lshl_add_u64 v[158:159], v[132:133], 0, v[154:155]
	v_cndmask_b32_e64 v131, 0, 1, s[30:31]
	v_cmp_ne_u32_e64 s[6:7], 1, v131
	s_andn2_b64 vcc, exec, s[30:31]
	v_lshl_add_u64 v[170:171], v[158:159], 2, s[38:39]
	v_mov_b32_e32 v131, 0
	v_mov_b32_e32 v132, 0
	v_mov_b32_e32 v133, 0
	v_mov_b32_e32 v134, 0
	v_mov_b32_e32 v135, 0
	v_mov_b32_e32 v136, 0
	v_mov_b32_e32 v137, 0
	s_cbranch_vccnz .LBB0_1583
	global_load_dwordx4 v[130:133], v[170:171], off
	global_load_dwordx4 v[134:137], v[170:171], off offset:16
	s_waitcnt vmcnt(0)
.LBB0_1583:
	v_add_u32_e32 v156, s28, v1
	v_pk_fma_f32 v[76:77], v[76:77], v[196:197], v[132:133]
	v_pk_fma_f32 v[74:75], v[74:75], v[192:193], v[130:131]
	v_pk_fma_f32 v[80:81], v[80:81], v[186:187], v[136:137]
	v_pk_fma_f32 v[78:79], v[78:79], v[182:183], v[134:135]
	v_lshl_add_u64 v[178:179], v[158:159], 2, s[36:37]
	s_and_b64 vcc, exec, s[4:5]
	v_ashrrev_i32_e32 v157, 31, v156
	global_store_dwordx4 v[178:179], v[74:77], off
	global_store_dwordx4 v[178:179], v[78:81], off offset:16
	s_cbranch_vccnz .LBB0_1585
	v_pk_mul_f32 v[132:133], v[220:221], v[76:77]
	v_pk_mul_f32 v[130:131], v[218:219], v[74:75]
	v_pk_mul_f32 v[134:135], v[216:217], v[80:81]
	v_cvt_pk_bf16_f32 v130, v130, v131
	v_cvt_pk_bf16_f32 v131, v132, v133
	v_cvt_pk_bf16_f32 v133, v134, v135
	v_lshlrev_b64 v[134:135], 11, v[156:157]
	v_pk_mul_f32 v[136:137], v[214:215], v[78:79]
	v_lshl_add_u64 v[134:135], s[16:17], 0, v[134:135]
	v_cvt_pk_bf16_f32 v132, v136, v137
	v_lshl_add_u64 v[134:135], v[154:155], 1, v[134:135]
	global_store_dwordx4 v[134:135], v[130:133], off
.LBB0_1585:
	s_nop 1
	v_or_b32_e32 v130, 16, v184
	v_ashrrev_i32_e32 v131, 31, v130
	v_lshlrev_b64 v[130:131], 10, v[130:131]
	v_lshl_add_u64 v[160:161], v[130:131], 0, v[154:155]
	v_mov_b32_e32 v134, 0
	s_and_b64 vcc, exec, s[6:7]
	v_lshl_add_u64 v[174:175], v[160:161], 2, s[38:39]
	v_mov_b32_e32 v135, 0
	v_mov_b32_e32 v136, 0
	v_mov_b32_e32 v137, 0
	v_mov_b32_e32 v130, 0
	v_mov_b32_e32 v131, 0
	v_mov_b32_e32 v132, 0
	v_mov_b32_e32 v133, 0
	s_cbranch_vccnz .LBB0_1587
	global_load_dwordx4 v[134:137], v[174:175], off
	global_load_dwordx4 v[130:133], v[174:175], off offset:16
	s_waitcnt vmcnt(0)
.LBB0_1587:
	v_add_u32_e32 v158, s28, v237
	v_pk_fma_f32 v[92:93], v[92:93], v[196:197], v[136:137]
	v_pk_fma_f32 v[90:91], v[90:91], v[192:193], v[134:135]
	v_pk_fma_f32 v[96:97], v[96:97], v[186:187], v[132:133]
	v_pk_fma_f32 v[94:95], v[94:95], v[182:183], v[130:131]
	v_lshl_add_u64 v[188:189], v[160:161], 2, s[36:37]
	s_and_b64 vcc, exec, s[4:5]
	v_ashrrev_i32_e32 v159, 31, v158
	global_store_dwordx4 v[188:189], v[90:93], off
	global_store_dwordx4 v[188:189], v[94:97], off offset:16
	s_cbranch_vccnz .LBB0_1589
	v_pk_mul_f32 v[132:133], v[220:221], v[92:93]
	v_pk_mul_f32 v[130:131], v[218:219], v[90:91]
	v_pk_mul_f32 v[134:135], v[216:217], v[96:97]
	v_cvt_pk_bf16_f32 v130, v130, v131
	v_cvt_pk_bf16_f32 v131, v132, v133
	v_cvt_pk_bf16_f32 v133, v134, v135
	v_lshlrev_b64 v[134:135], 11, v[158:159]
	v_pk_mul_f32 v[136:137], v[214:215], v[94:95]
	v_lshl_add_u64 v[134:135], s[16:17], 0, v[134:135]
	v_cvt_pk_bf16_f32 v132, v136, v137
	v_lshl_add_u64 v[134:135], v[154:155], 1, v[134:135]
	global_store_dwordx4 v[134:135], v[130:133], off
.LBB0_1589:
	s_nop 1
	v_or_b32_e32 v130, 32, v184
	v_ashrrev_i32_e32 v131, 31, v130
	v_lshlrev_b64 v[130:131], 10, v[130:131]
	v_lshl_add_u64 v[166:167], v[130:131], 0, v[154:155]
	v_mov_b32_e32 v134, 0
	s_and_b64 vcc, exec, s[6:7]
	v_lshl_add_u64 v[180:181], v[166:167], 2, s[38:39]
	v_mov_b32_e32 v135, 0
	v_mov_b32_e32 v136, 0
	v_mov_b32_e32 v137, 0
	v_mov_b32_e32 v130, 0
	v_mov_b32_e32 v131, 0
	v_mov_b32_e32 v132, 0
	v_mov_b32_e32 v133, 0
	s_cbranch_vccnz .LBB0_1591
	global_load_dwordx4 v[134:137], v[180:181], off
	global_load_dwordx4 v[130:133], v[180:181], off offset:16
	s_waitcnt vmcnt(0)
.LBB0_1591:
	v_add_u32_e32 v160, s28, v238
	v_pk_fma_f32 v[100:101], v[100:101], v[196:197], v[136:137]
	v_pk_fma_f32 v[98:99], v[98:99], v[192:193], v[134:135]
	v_pk_fma_f32 v[104:105], v[104:105], v[186:187], v[132:133]
	v_pk_fma_f32 v[102:103], v[102:103], v[182:183], v[130:131]
	v_lshl_add_u64 v[194:195], v[166:167], 2, s[36:37]
	s_and_b64 vcc, exec, s[4:5]
	v_ashrrev_i32_e32 v161, 31, v160
	global_store_dwordx4 v[194:195], v[98:101], off
	global_store_dwordx4 v[194:195], v[102:105], off offset:16
	s_cbranch_vccnz .LBB0_1593
	v_pk_mul_f32 v[132:133], v[220:221], v[100:101]
	v_pk_mul_f32 v[130:131], v[218:219], v[98:99]
	v_pk_mul_f32 v[134:135], v[216:217], v[104:105]
	v_cvt_pk_bf16_f32 v130, v130, v131
	v_cvt_pk_bf16_f32 v131, v132, v133
	v_cvt_pk_bf16_f32 v133, v134, v135
	v_lshlrev_b64 v[134:135], 11, v[160:161]
	v_pk_mul_f32 v[136:137], v[214:215], v[102:103]
	v_lshl_add_u64 v[134:135], s[16:17], 0, v[134:135]
	v_cvt_pk_bf16_f32 v132, v136, v137
	v_lshl_add_u64 v[134:135], v[154:155], 1, v[134:135]
	global_store_dwordx4 v[134:135], v[130:133], off
.LBB0_1593:
	s_nop 1
	v_or_b32_e32 v130, 48, v184
	v_ashrrev_i32_e32 v131, 31, v130
	v_lshlrev_b64 v[130:131], 10, v[130:131]
	v_lshl_add_u64 v[168:169], v[130:131], 0, v[154:155]
	v_mov_b32_e32 v134, 0
	s_and_b64 vcc, exec, s[6:7]
	v_lshl_add_u64 v[190:191], v[168:169], 2, s[38:39]
	v_mov_b32_e32 v135, 0
	v_mov_b32_e32 v136, 0
	v_mov_b32_e32 v137, 0
	v_mov_b32_e32 v130, 0
	v_mov_b32_e32 v131, 0
	v_mov_b32_e32 v132, 0
	v_mov_b32_e32 v133, 0
	s_cbranch_vccnz .LBB0_1595
	global_load_dwordx4 v[134:137], v[190:191], off
	global_load_dwordx4 v[130:133], v[190:191], off offset:16
	s_waitcnt vmcnt(0)
.LBB0_1595:
	v_add_u32_e32 v166, s28, v239
	v_pk_fma_f32 v[116:117], v[116:117], v[196:197], v[136:137]
	v_pk_fma_f32 v[114:115], v[114:115], v[192:193], v[134:135]
	v_pk_fma_f32 v[120:121], v[120:121], v[186:187], v[132:133]
	v_pk_fma_f32 v[118:119], v[118:119], v[182:183], v[130:131]
	v_lshl_add_u64 v[200:201], v[168:169], 2, s[36:37]
	s_and_b64 vcc, exec, s[4:5]
	v_ashrrev_i32_e32 v167, 31, v166
	global_store_dwordx4 v[200:201], v[114:117], off
	global_store_dwordx4 v[200:201], v[118:121], off offset:16
	s_cbranch_vccnz .LBB0_1597
	v_pk_mul_f32 v[132:133], v[220:221], v[116:117]
	v_pk_mul_f32 v[130:131], v[218:219], v[114:115]
	v_pk_mul_f32 v[134:135], v[216:217], v[120:121]
	v_cvt_pk_bf16_f32 v130, v130, v131
	v_cvt_pk_bf16_f32 v131, v132, v133
	v_cvt_pk_bf16_f32 v133, v134, v135
	v_lshlrev_b64 v[134:135], 11, v[166:167]
	v_pk_mul_f32 v[136:137], v[214:215], v[118:119]
	v_lshl_add_u64 v[134:135], s[16:17], 0, v[134:135]
	v_cvt_pk_bf16_f32 v132, v136, v137
	v_lshl_add_u64 v[134:135], v[154:155], 1, v[134:135]
	global_store_dwordx4 v[134:135], v[130:133], off
.LBB0_1597:
	s_nop 1
	v_add_u32_e32 v130, 0x80, v184
	v_ashrrev_i32_e32 v131, 31, v130
	v_lshlrev_b64 v[130:131], 10, v[130:131]
	v_lshl_add_u64 v[172:173], v[130:131], 0, v[154:155]
	v_mov_b32_e32 v134, 0
	s_and_b64 vcc, exec, s[6:7]
	v_lshl_add_u64 v[198:199], v[172:173], 2, s[38:39]
	v_mov_b32_e32 v135, 0
	v_mov_b32_e32 v136, 0
	v_mov_b32_e32 v137, 0
	v_mov_b32_e32 v130, 0
	v_mov_b32_e32 v131, 0
	v_mov_b32_e32 v132, 0
	v_mov_b32_e32 v133, 0
	s_cbranch_vccnz .LBB0_1599
	global_load_dwordx4 v[134:137], v[198:199], off
	global_load_dwordx4 v[130:133], v[198:199], off offset:16
	s_waitcnt vmcnt(0)
.LBB0_1599:
	v_add_u32_e32 v168, s28, v240
	v_pk_fma_f32 v[124:125], v[124:125], v[196:197], v[136:137]
	v_pk_fma_f32 v[122:123], v[122:123], v[192:193], v[134:135]
	v_pk_fma_f32 v[128:129], v[128:129], v[186:187], v[132:133]
	v_pk_fma_f32 v[126:127], v[126:127], v[182:183], v[130:131]
	v_lshl_add_u64 v[204:205], v[172:173], 2, s[36:37]
	s_and_b64 vcc, exec, s[4:5]
	v_ashrrev_i32_e32 v169, 31, v168
	global_store_dwordx4 v[204:205], v[122:125], off
	global_store_dwordx4 v[204:205], v[126:129], off offset:16
	s_cbranch_vccnz .LBB0_1601
	v_pk_mul_f32 v[132:133], v[220:221], v[124:125]
	v_pk_mul_f32 v[130:131], v[218:219], v[122:123]
	v_pk_mul_f32 v[134:135], v[216:217], v[128:129]
	v_cvt_pk_bf16_f32 v130, v130, v131
	v_cvt_pk_bf16_f32 v131, v132, v133
	v_cvt_pk_bf16_f32 v133, v134, v135
	v_lshlrev_b64 v[134:135], 11, v[168:169]
	v_pk_mul_f32 v[136:137], v[214:215], v[126:127]
	v_lshl_add_u64 v[134:135], s[16:17], 0, v[134:135]
	v_cvt_pk_bf16_f32 v132, v136, v137
	v_lshl_add_u64 v[134:135], v[154:155], 1, v[134:135]
	global_store_dwordx4 v[134:135], v[130:133], off
.LBB0_1601:
	s_nop 1
	v_add_u32_e32 v130, 0x90, v184
	v_ashrrev_i32_e32 v131, 31, v130
	v_lshlrev_b64 v[130:131], 10, v[130:131]
	v_lshl_add_u64 v[176:177], v[130:131], 0, v[154:155]
	v_mov_b32_e32 v134, 0
	s_and_b64 vcc, exec, s[6:7]
	v_lshl_add_u64 v[202:203], v[176:177], 2, s[38:39]
	v_mov_b32_e32 v135, 0
	v_mov_b32_e32 v136, 0
	v_mov_b32_e32 v137, 0
	v_mov_b32_e32 v130, 0
	v_mov_b32_e32 v131, 0
	v_mov_b32_e32 v132, 0
	v_mov_b32_e32 v133, 0
	s_cbranch_vccnz .LBB0_1603
	global_load_dwordx4 v[134:137], v[202:203], off
	global_load_dwordx4 v[130:133], v[202:203], off offset:16
	s_waitcnt vmcnt(0)
.LBB0_1603:
	v_add_u32_e32 v172, s28, v241
	v_pk_fma_f32 v[112:113], v[112:113], v[196:197], v[136:137]
	v_pk_fma_f32 v[110:111], v[110:111], v[192:193], v[134:135]
	v_pk_fma_f32 v[108:109], v[108:109], v[186:187], v[132:133]
	v_pk_fma_f32 v[106:107], v[106:107], v[182:183], v[130:131]
	v_lshl_add_u64 v[208:209], v[176:177], 2, s[36:37]
	s_and_b64 vcc, exec, s[4:5]
	v_ashrrev_i32_e32 v173, 31, v172
	global_store_dwordx4 v[208:209], v[110:113], off
	global_store_dwordx4 v[208:209], v[106:109], off offset:16
	s_cbranch_vccnz .LBB0_1605
	v_pk_mul_f32 v[132:133], v[220:221], v[112:113]
	v_pk_mul_f32 v[130:131], v[218:219], v[110:111]
	v_pk_mul_f32 v[134:135], v[216:217], v[108:109]
	v_cvt_pk_bf16_f32 v130, v130, v131
	v_cvt_pk_bf16_f32 v131, v132, v133
	v_cvt_pk_bf16_f32 v133, v134, v135
	v_lshlrev_b64 v[134:135], 11, v[172:173]
	v_pk_mul_f32 v[136:137], v[214:215], v[106:107]
	v_lshl_add_u64 v[134:135], s[16:17], 0, v[134:135]
	v_cvt_pk_bf16_f32 v132, v136, v137
	v_lshl_add_u64 v[134:135], v[154:155], 1, v[134:135]
	global_store_dwordx4 v[134:135], v[130:133], off
.LBB0_1605:
	s_nop 1
	v_add_u32_e32 v130, 0xa0, v184
	v_ashrrev_i32_e32 v131, 31, v130
	v_lshlrev_b64 v[130:131], 10, v[130:131]
	v_lshl_add_u64 v[210:211], v[130:131], 0, v[154:155]
	v_mov_b32_e32 v134, 0
	s_and_b64 vcc, exec, s[6:7]
	v_lshl_add_u64 v[206:207], v[210:211], 2, s[38:39]
	v_mov_b32_e32 v135, 0
	v_mov_b32_e32 v136, 0
	v_mov_b32_e32 v137, 0
	v_mov_b32_e32 v130, 0
	v_mov_b32_e32 v131, 0
	v_mov_b32_e32 v132, 0
	v_mov_b32_e32 v133, 0
	s_cbranch_vccnz .LBB0_1607
	global_load_dwordx4 v[134:137], v[206:207], off
	global_load_dwordx4 v[130:133], v[206:207], off offset:16
	s_waitcnt vmcnt(0)
.LBB0_1607:
	v_add_u32_e32 v176, s28, v242
	v_pk_fma_f32 v[88:89], v[88:89], v[196:197], v[136:137]
	v_pk_fma_f32 v[86:87], v[86:87], v[192:193], v[134:135]
	v_pk_fma_f32 v[84:85], v[84:85], v[186:187], v[132:133]
	v_pk_fma_f32 v[82:83], v[82:83], v[182:183], v[130:131]
	v_lshl_add_u64 v[212:213], v[210:211], 2, s[36:37]
	s_and_b64 vcc, exec, s[4:5]
	v_ashrrev_i32_e32 v177, 31, v176
	global_store_dwordx4 v[212:213], v[86:89], off
	global_store_dwordx4 v[212:213], v[82:85], off offset:16
	s_cbranch_vccnz .LBB0_1609
	v_pk_mul_f32 v[132:133], v[220:221], v[88:89]
	v_pk_mul_f32 v[130:131], v[218:219], v[86:87]
	v_pk_mul_f32 v[134:135], v[216:217], v[84:85]
	v_cvt_pk_bf16_f32 v130, v130, v131
	v_cvt_pk_bf16_f32 v131, v132, v133
	v_cvt_pk_bf16_f32 v133, v134, v135
	v_lshlrev_b64 v[134:135], 11, v[176:177]
	v_pk_mul_f32 v[136:137], v[214:215], v[82:83]
	v_lshl_add_u64 v[134:135], s[16:17], 0, v[134:135]
	v_cvt_pk_bf16_f32 v132, v136, v137
	v_lshl_add_u64 v[134:135], v[154:155], 1, v[134:135]
	global_store_dwordx4 v[134:135], v[130:133], off
.LBB0_1609:
	s_nop 1
	v_add_u32_e32 v130, 0xb0, v184
	v_ashrrev_i32_e32 v131, 31, v130
	v_lshlrev_b64 v[130:131], 10, v[130:131]
	v_lshl_add_u64 v[222:223], v[130:131], 0, v[154:155]
	v_mov_b32_e32 v134, 0
	s_and_b64 vcc, exec, s[6:7]
	v_lshl_add_u64 v[210:211], v[222:223], 2, s[38:39]
	v_mov_b32_e32 v135, 0
	v_mov_b32_e32 v136, 0
	v_mov_b32_e32 v137, 0
	v_mov_b32_e32 v130, 0
	v_mov_b32_e32 v131, 0
	v_mov_b32_e32 v132, 0
	v_mov_b32_e32 v133, 0
	s_cbranch_vccnz .LBB0_1611
	global_load_dwordx4 v[134:137], v[210:211], off
	global_load_dwordx4 v[130:133], v[210:211], off offset:16
	s_waitcnt vmcnt(0)
.LBB0_1611:
	v_add_u32_e32 v184, s28, v243
	v_pk_fma_f32 v[72:73], v[72:73], v[196:197], v[136:137]
	v_pk_fma_f32 v[70:71], v[70:71], v[192:193], v[134:135]
	v_pk_fma_f32 v[68:69], v[68:69], v[186:187], v[132:133]
	v_pk_fma_f32 v[66:67], v[66:67], v[182:183], v[130:131]
	v_lshl_add_u64 v[182:183], v[222:223], 2, s[36:37]
	s_and_b64 vcc, exec, s[4:5]
	v_ashrrev_i32_e32 v185, 31, v184
	global_store_dwordx4 v[182:183], v[70:73], off
	global_store_dwordx4 v[182:183], v[66:69], off offset:16
	s_cbranch_vccnz .LBB0_1613
	v_pk_mul_f32 v[132:133], v[220:221], v[72:73]
	v_pk_mul_f32 v[130:131], v[218:219], v[70:71]
	v_pk_mul_f32 v[134:135], v[216:217], v[68:69]
	v_cvt_pk_bf16_f32 v130, v130, v131
	v_cvt_pk_bf16_f32 v131, v132, v133
	v_cvt_pk_bf16_f32 v133, v134, v135
	v_lshlrev_b64 v[134:135], 11, v[184:185]
	v_pk_mul_f32 v[136:137], v[214:215], v[66:67]
	v_lshl_add_u64 v[134:135], s[16:17], 0, v[134:135]
	v_cvt_pk_bf16_f32 v132, v136, v137
	v_lshl_add_u64 v[134:135], v[154:155], 1, v[134:135]
	global_store_dwordx4 v[134:135], v[130:133], off

.LBB0_1619:
	v_pk_fma_f32 v[64:65], v[64:65], v[214:215], v[132:133]
	v_pk_fma_f32 v[62:63], v[62:63], v[196:197], v[130:131]
	v_pk_fma_f32 v[60:61], v[60:61], v[192:193], v[136:137]
	v_pk_fma_f32 v[58:59], v[58:59], v[186:187], v[134:135]
	s_and_b64 vcc, exec, s[4:5]
	global_store_dwordx4 v[178:179], v[62:65], off offset:512
	global_store_dwordx4 v[178:179], v[58:61], off offset:528
	s_cbranch_vccnz .LBB0_1621
	v_pk_mul_f32 v[132:133], v[222:223], v[64:65]
	v_pk_mul_f32 v[130:131], v[220:221], v[62:63]
	v_pk_mul_f32 v[134:135], v[218:219], v[60:61]
	v_cvt_pk_bf16_f32 v130, v130, v131
	v_cvt_pk_bf16_f32 v131, v132, v133
	v_cvt_pk_bf16_f32 v133, v134, v135
	v_lshlrev_b64 v[134:135], 11, v[156:157]
	v_pk_mul_f32 v[136:137], v[216:217], v[58:59]
	v_lshl_add_u64 v[134:135], s[16:17], 0, v[134:135]
	v_cvt_pk_bf16_f32 v132, v136, v137
	v_lshl_add_u64 v[134:135], v[154:155], 1, v[134:135]
	global_store_dwordx4 v[134:135], v[130:133], off offset:256

.LBB0_1623:
	v_pk_fma_f32 v[56:57], v[56:57], v[214:215], v[136:137]
	v_pk_fma_f32 v[54:55], v[54:55], v[196:197], v[134:135]
	v_pk_fma_f32 v[52:53], v[52:53], v[192:193], v[132:133]
	v_pk_fma_f32 v[50:51], v[50:51], v[186:187], v[130:131]
	s_and_b64 vcc, exec, s[4:5]
	global_store_dwordx4 v[188:189], v[54:57], off offset:512
	global_store_dwordx4 v[188:189], v[50:53], off offset:528
	s_cbranch_vccnz .LBB0_1625
	v_pk_mul_f32 v[132:133], v[222:223], v[56:57]
	v_pk_mul_f32 v[130:131], v[220:221], v[54:55]
	v_pk_mul_f32 v[134:135], v[218:219], v[52:53]
	v_cvt_pk_bf16_f32 v130, v130, v131
	v_cvt_pk_bf16_f32 v131, v132, v133
	v_cvt_pk_bf16_f32 v133, v134, v135
	v_lshlrev_b64 v[134:135], 11, v[158:159]
	v_pk_mul_f32 v[136:137], v[216:217], v[50:51]
	v_lshl_add_u64 v[134:135], s[16:17], 0, v[134:135]
	v_cvt_pk_bf16_f32 v132, v136, v137
	v_lshl_add_u64 v[134:135], v[154:155], 1, v[134:135]
	global_store_dwordx4 v[134:135], v[130:133], off offset:256

.LBB0_1627:
	v_pk_fma_f32 v[48:49], v[48:49], v[214:215], v[136:137]
	v_pk_fma_f32 v[46:47], v[46:47], v[196:197], v[134:135]
	v_pk_fma_f32 v[44:45], v[44:45], v[192:193], v[132:133]
	v_pk_fma_f32 v[42:43], v[42:43], v[186:187], v[130:131]
	s_and_b64 vcc, exec, s[4:5]
	global_store_dwordx4 v[194:195], v[46:49], off offset:512
	global_store_dwordx4 v[194:195], v[42:45], off offset:528
	s_cbranch_vccnz .LBB0_1629
	v_pk_mul_f32 v[132:133], v[222:223], v[48:49]
	v_pk_mul_f32 v[130:131], v[220:221], v[46:47]
	v_pk_mul_f32 v[134:135], v[218:219], v[44:45]
	v_cvt_pk_bf16_f32 v130, v130, v131
	v_cvt_pk_bf16_f32 v131, v132, v133
	v_cvt_pk_bf16_f32 v133, v134, v135
	v_lshlrev_b64 v[134:135], 11, v[160:161]
	v_pk_mul_f32 v[136:137], v[216:217], v[42:43]
	v_lshl_add_u64 v[134:135], s[16:17], 0, v[134:135]
	v_cvt_pk_bf16_f32 v132, v136, v137
	v_lshl_add_u64 v[134:135], v[154:155], 1, v[134:135]
	global_store_dwordx4 v[134:135], v[130:133], off offset:256

.LBB0_1631:
	v_pk_fma_f32 v[40:41], v[40:41], v[214:215], v[136:137]
	v_pk_fma_f32 v[38:39], v[38:39], v[196:197], v[134:135]
	v_pk_fma_f32 v[36:37], v[36:37], v[192:193], v[132:133]
	v_pk_fma_f32 v[34:35], v[34:35], v[186:187], v[130:131]
	s_and_b64 vcc, exec, s[4:5]
	global_store_dwordx4 v[200:201], v[38:41], off offset:512
	global_store_dwordx4 v[200:201], v[34:37], off offset:528
	s_cbranch_vccnz .LBB0_1633
	v_pk_mul_f32 v[132:133], v[222:223], v[40:41]
	v_pk_mul_f32 v[130:131], v[220:221], v[38:39]
	v_pk_mul_f32 v[134:135], v[218:219], v[36:37]
	v_cvt_pk_bf16_f32 v130, v130, v131
	v_cvt_pk_bf16_f32 v131, v132, v133
	v_cvt_pk_bf16_f32 v133, v134, v135
	v_lshlrev_b64 v[134:135], 11, v[166:167]
	v_pk_mul_f32 v[136:137], v[216:217], v[34:35]
	v_lshl_add_u64 v[134:135], s[16:17], 0, v[134:135]
	v_cvt_pk_bf16_f32 v132, v136, v137
	v_lshl_add_u64 v[134:135], v[154:155], 1, v[134:135]
	global_store_dwordx4 v[134:135], v[130:133], off offset:256

.LBB0_1635:
	v_pk_fma_f32 v[32:33], v[32:33], v[214:215], v[136:137]
	v_pk_fma_f32 v[30:31], v[30:31], v[196:197], v[134:135]
	v_pk_fma_f32 v[28:29], v[28:29], v[192:193], v[132:133]
	v_pk_fma_f32 v[26:27], v[26:27], v[186:187], v[130:131]
	s_and_b64 vcc, exec, s[4:5]
	global_store_dwordx4 v[204:205], v[30:33], off offset:512
	global_store_dwordx4 v[204:205], v[26:29], off offset:528
	s_cbranch_vccnz .LBB0_1637
	v_pk_mul_f32 v[132:133], v[222:223], v[32:33]
	v_pk_mul_f32 v[130:131], v[220:221], v[30:31]
	v_pk_mul_f32 v[134:135], v[218:219], v[28:29]
	v_cvt_pk_bf16_f32 v130, v130, v131
	v_cvt_pk_bf16_f32 v131, v132, v133
	v_cvt_pk_bf16_f32 v133, v134, v135
	v_lshlrev_b64 v[134:135], 11, v[168:169]
	v_pk_mul_f32 v[136:137], v[216:217], v[26:27]
	v_lshl_add_u64 v[134:135], s[16:17], 0, v[134:135]
	v_cvt_pk_bf16_f32 v132, v136, v137
	v_lshl_add_u64 v[134:135], v[154:155], 1, v[134:135]
	global_store_dwordx4 v[134:135], v[130:133], off offset:256

.LBB0_1639:
	v_pk_fma_f32 v[24:25], v[24:25], v[214:215], v[136:137]
	v_pk_fma_f32 v[22:23], v[22:23], v[196:197], v[134:135]
	v_pk_fma_f32 v[20:21], v[20:21], v[192:193], v[132:133]
	v_pk_fma_f32 v[18:19], v[18:19], v[186:187], v[130:131]
	s_and_b64 vcc, exec, s[4:5]
	global_store_dwordx4 v[208:209], v[22:25], off offset:512
	global_store_dwordx4 v[208:209], v[18:21], off offset:528
	s_cbranch_vccnz .LBB0_1641
	v_pk_mul_f32 v[132:133], v[222:223], v[24:25]
	v_pk_mul_f32 v[130:131], v[220:221], v[22:23]
	v_pk_mul_f32 v[134:135], v[218:219], v[20:21]
	v_cvt_pk_bf16_f32 v130, v130, v131
	v_cvt_pk_bf16_f32 v131, v132, v133
	v_cvt_pk_bf16_f32 v133, v134, v135
	v_lshlrev_b64 v[134:135], 11, v[172:173]
	v_pk_mul_f32 v[136:137], v[216:217], v[18:19]
	v_lshl_add_u64 v[134:135], s[16:17], 0, v[134:135]
	v_cvt_pk_bf16_f32 v132, v136, v137
	v_lshl_add_u64 v[134:135], v[154:155], 1, v[134:135]
	global_store_dwordx4 v[134:135], v[130:133], off offset:256

.LBB0_1643:
	v_pk_fma_f32 v[16:17], v[16:17], v[214:215], v[136:137]
	v_pk_fma_f32 v[14:15], v[14:15], v[196:197], v[134:135]
	v_pk_fma_f32 v[12:13], v[12:13], v[192:193], v[132:133]
	v_pk_fma_f32 v[10:11], v[10:11], v[186:187], v[130:131]
	s_and_b64 vcc, exec, s[4:5]
	global_store_dwordx4 v[212:213], v[14:17], off offset:512
	global_store_dwordx4 v[212:213], v[10:13], off offset:528
	s_cbranch_vccnz .LBB0_1645
	v_pk_mul_f32 v[132:133], v[222:223], v[16:17]
	v_pk_mul_f32 v[130:131], v[220:221], v[14:15]
	v_pk_mul_f32 v[134:135], v[218:219], v[12:13]
	v_cvt_pk_bf16_f32 v130, v130, v131
	v_cvt_pk_bf16_f32 v131, v132, v133
	v_cvt_pk_bf16_f32 v133, v134, v135
	v_lshlrev_b64 v[134:135], 11, v[176:177]
	v_pk_mul_f32 v[136:137], v[216:217], v[10:11]
	v_lshl_add_u64 v[134:135], s[16:17], 0, v[134:135]
	v_cvt_pk_bf16_f32 v132, v136, v137
	v_lshl_add_u64 v[134:135], v[154:155], 1, v[134:135]
	global_store_dwordx4 v[134:135], v[130:133], off offset:256

.LBB0_1647:
	v_pk_fma_f32 v[8:9], v[8:9], v[214:215], v[136:137]
	v_pk_fma_f32 v[6:7], v[6:7], v[196:197], v[134:135]
	v_pk_fma_f32 v[4:5], v[4:5], v[192:193], v[132:133]
	v_pk_fma_f32 v[2:3], v[2:3], v[186:187], v[130:131]
	s_and_b64 vcc, exec, s[4:5]
	global_store_dwordx4 v[182:183], v[6:9], off offset:512
	global_store_dwordx4 v[182:183], v[2:5], off offset:528
	s_cbranch_vccnz .LBB0_1650
	v_pk_mul_f32 v[132:133], v[222:223], v[8:9]
	v_pk_mul_f32 v[130:131], v[220:221], v[6:7]
	v_pk_mul_f32 v[134:135], v[218:219], v[4:5]
	v_cvt_pk_bf16_f32 v130, v130, v131
	v_cvt_pk_bf16_f32 v131, v132, v133
	v_cvt_pk_bf16_f32 v133, v134, v135
	v_lshlrev_b64 v[134:135], 11, v[184:185]
	v_pk_mul_f32 v[136:137], v[216:217], v[2:3]
	v_lshl_add_u64 v[134:135], s[16:17], 0, v[134:135]
	v_cvt_pk_bf16_f32 v132, v136, v137
	v_lshl_add_u64 v[134:135], v[154:155], 1, v[134:135]
	global_store_dwordx4 v[134:135], v[130:133], off offset:256
	s_and_b64 vcc, exec, s[30:31]
	s_cbranch_vccnz .LBB0_1651
